# attention step loops: single-copy permlane max reduction, loop-invariant lane/query index copies forwarded, lane>>4 hoisted per unit
# speedup vs baseline: 1.0262x; 1.0066x over previous
; template <int NT>
; __device__ void attn_unitN(const P& p, int u) {
;     ...
;   int lane = opaque_tid(p) & 63, q = lane & 15, quad = lane >> 4;
;   int rb = u % RS, h = (u / RS) & 7, span = u / (RS * 8);
;   int tb = span * 256;
;   int seq0, L;
;   if (tb < NT_P) { L = 4096; seq0 = tb & ~4095; } else { L = 8192; seq0 = NT_P + ((tb - NT_P) & ~8191); }
;   int L16 = L >> 4;
;   int i0 = (tb - seq0) >> 4;
;   int iq = i0 + q;
;   const u16* Qd = (const u16*)((const char*)p.out + OUT_QD);
;   const u16* Kd = (const u16*)((const char*)p.out + OUT_KD);
;   const u16* VdT = (const u16*)(p.ws + OFF_VDT);
;   extern __shared__ __attribute__((aligned(16))) u16 shm[];
;   bf16x8* qs = (bf16x8*)((char*)shm + __builtin_amdgcn_readfirstlane(opaque_tid(p) >> 6) * 8192) + lane;
;   f32x4 o[NT][4];
;   float mrun[NT], lrun[NT];
; #pragma unroll
;   for (int t = 0; t < NT; ++t) {
;     const u16* qp = Qd + (size_t)(seq0 + rb + RS * t + 16 * iq) * 512 + h * 64 + quad * 16;
;     qs[t * 128] = *(const bf16x8*)qp; qs[t * 128 + 64] = *(const bf16x8*)(qp + 8);
; #pragma unroll
;     for (int dt = 0; dt < 4; ++dt) o[t][dt] = f32x4{0.f, 0.f, 0.f, 0.f};
;     mrun[t] = -1e30f; lrun[t] = 0.f;
;   }
;   const u16* kbase = Kd + (size_t)seq0 * 512 + h * 64 + quad * 16;
;   const u16* vbase = VdT + (size_t)seq0 * 512 + (size_t)h * 16 * 64 * L16;
;   KVB bA = attn_load_e<NT>(0, kbase, vbase, L16, rb, i0, lane);
;   KVB bB = attn_load_e<NT>(1, kbase, vbase, L16, rb, i0, lane);
.LBB0_231:
	s_ashr_i32 s0, s3, 31
	s_lshr_b32 s1, s0, 30
	s_lshr_b32 s0, s0, 27
	s_add_i32 s1, s3, s1
	s_add_i32 s0, s3, s0
	s_and_b32 s4, s1, -4
	s_lshl_b32 s0, s0, 3
	s_sub_i32 s42, s3, s4
	s_bfe_u32 s8, s1, 0x30002
	s_and_b32 s1, s0, 0xffffff00
	s_cmpk_lt_i32 s3, 0x1000
	s_cselect_b32 s0, s31, 0x7fffe000
	v_mbcnt_lo_u32_b32 v224, -1, 0
	v_mbcnt_hi_u32_b32 v224, -1, v224
	s_cselect_b32 s10, 8, 9
	s_cselect_b32 s43, s40, 0x1ff
	s_cselect_b32 s44, 6, 7
	s_and_b32 s0, s1, s0
	v_mbcnt_lo_u32_b32 v0, -1, 0
	v_mbcnt_hi_u32_b32 v0, -1, v0
	s_sub_i32 s1, s1, s0
	v_add_u32_e32 v0, s33, v0
	s_ashr_i32 s46, s1, 4
	v_readfirstlane_b32 s1, v0
	v_and_b32_e32 v34, 15, v224
	s_lshl_b32 s1, s1, 7
	v_or_b32_e32 v225, s46, v34
	s_and_b32 s1, s1, 0xffffe000
	s_add_i32 s4, s0, s42
	s_add_i32 s1, s1, 16
	v_lshl_add_u32 v152, v225, 4, s4
	s_lshl_b32 s45, s8, 6
	s_lshl_b32 s11, s8, 15
	s_add_u32 s4, s26, s11
	v_and_b32_e32 v0, 48, v224
	v_add_u32_e32 v150, 4, v152
	v_add_u32_e32 v148, 8, v152
	v_add_u32_e32 v146, 12, v152
	s_addc_u32 s5, s27, 0
	v_lshlrev_b32_e32 v144, 3, v0
	v_ashrrev_i32_e32 v153, 31, v152
	v_ashrrev_i32_e32 v151, 31, v150
	v_ashrrev_i32_e32 v149, 31, v148
	v_ashrrev_i32_e32 v147, 31, v146
	v_lshl_add_u64 v[24:25], s[4:5], 0, v[144:145]
	v_lshrrev_b32_e32 v243, 8, v152
	v_and_b32_e32 v244, 15, v152
	v_lshlrev_b32_e32 v243, 18, v243
	v_lshl_or_b32 v243, v244, 11, v243
	v_bfe_u32 v244, v152, 6, 2
	v_lshl_or_b32 v243, v244, 9, v243
	v_bfe_u32 v244, v152, 4, 2
	v_lshl_or_b32 v0, v244, 5, v243
	v_mov_b32_e32 v1, 0
	v_lshrrev_b32_e32 v243, 8, v150
	v_and_b32_e32 v244, 15, v150
	v_lshlrev_b32_e32 v243, 18, v243
	v_lshl_or_b32 v243, v244, 11, v243
	v_bfe_u32 v244, v150, 6, 2
	v_lshl_or_b32 v243, v244, 9, v243
	v_bfe_u32 v244, v150, 4, 2
	v_lshl_or_b32 v8, v244, 5, v243
	v_mov_b32_e32 v9, 0
	v_lshrrev_b32_e32 v243, 8, v148
	v_and_b32_e32 v244, 15, v148
	v_lshlrev_b32_e32 v243, 18, v243
	v_lshl_or_b32 v243, v244, 11, v243
	v_bfe_u32 v244, v148, 6, 2
	v_lshl_or_b32 v243, v244, 9, v243
	v_bfe_u32 v244, v148, 4, 2
	v_lshl_or_b32 v16, v244, 5, v243
	v_mov_b32_e32 v17, 0
	v_lshrrev_b32_e32 v243, 8, v146
	v_and_b32_e32 v244, 15, v146
	v_lshlrev_b32_e32 v243, 18, v243
	v_lshl_or_b32 v243, v244, 11, v243
	v_bfe_u32 v244, v146, 6, 2
	v_lshl_or_b32 v243, v244, 9, v243
	v_bfe_u32 v244, v146, 4, 2
	v_lshl_or_b32 v26, v244, 5, v243
	v_mov_b32_e32 v27, 0
	v_lshl_add_u64 v[4:5], v[24:25], 0, v[0:1]
	v_lshl_add_u64 v[12:13], v[24:25], 0, v[8:9]
	v_lshl_add_u64 v[20:21], v[24:25], 0, v[16:17]
	v_lshl_add_u64 v[28:29], v[24:25], 0, v[26:27]
	global_load_dwordx4 v[0:3], v[4:5], off
	s_nop 0
	global_load_dwordx4 v[4:7], v[4:5], off offset:16
	s_nop 0
	global_load_dwordx4 v[8:11], v[12:13], off
	s_nop 0
	global_load_dwordx4 v[12:15], v[12:13], off offset:16
	s_nop 0
	global_load_dwordx4 v[16:19], v[20:21], off
	s_nop 0
	global_load_dwordx4 v[20:23], v[20:21], off offset:16
	s_nop 0
	global_load_dwordx4 v[24:27], v[28:29], off
	s_nop 0
	global_load_dwordx4 v[28:31], v[28:29], off offset:16
	v_and_b32_e32 v226, 63, v224
	v_lshrrev_b32_e32 v246, 4, v226
	v_lshlrev_b32_e32 v247, 2, v246
	v_lshl_add_u32 v228, v226, 4, s1
	s_ashr_i32 s1, s0, 31
	s_lshl_b64 s[0:1], s[0:1], 10
	s_add_u32 s4, s28, s0
	s_addc_u32 s5, s29, s1
	s_add_u32 s4, s4, s11
	s_addc_u32 s5, s5, 0
	s_add_u32 s0, s90, s0
	v_lshl_add_u64 v[154:155], s[4:5], 0, v[144:145]
	s_addc_u32 s1, s91, s1
	s_lshl_b32 s4, s8, 10
	s_lshl_b32 s4, s4, s10
	s_lshl_b32 s4, s4, 1
	s_add_u32 s0, s0, s4
	v_and_b32_e32 v227, 3, v224
	s_addc_u32 s1, s1, 0
	s_add_i32 s11, s46, -4
	v_or_b32_e32 v32, s11, v227
	v_max_i32_e32 v33, 0, v32
	v_max_i32_e32 v32, -4, v32
	v_min_i32_e32 v33, s43, v33
	v_add_u32_e32 v32, 4, v32
	v_bfe_u32 v239, v224, 2, 2
	v_min_u32_e32 v35, s43, v32
	v_lshlrev_b32_e32 v36, 4, v33
	v_or_b32_e32 v32, v36, v239
	v_lshrrev_b32_e32 v243, 8, v32
	v_and_b32_e32 v244, 15, v32
	v_lshlrev_b32_e32 v243, 18, v243
	v_lshl_or_b32 v243, v244, 11, v243
	v_bfe_u32 v244, v32, 6, 2
	v_lshl_or_b32 v243, v244, 9, v243
	v_bfe_u32 v244, v32, 4, 2
	v_lshl_or_b32 v144, v244, 5, v243
	v_bfe_u32 v238, v224, 4, 2
	v_lshl_add_u64 v[32:33], v[154:155], 0, v[144:145]
	s_ashr_i32 s4, s11, 2
	s_ashr_i32 s5, s4, 31
	v_lshlrev_b32_e32 v240, 3, v239
	v_lshlrev_b32_e32 v241, 3, v238
	s_movk_i32 s57, 0xff90
	s_add_i32 s47, s46, 0xffffff90
	s_add_i32 s56, s42, 4
	s_add_i32 s8, s42, 8
	s_add_i32 s10, s42, 12
	v_mov_b32_e32 v235, 0xf149f2ca
	s_mov_b32 s58, 4
	s_mov_b32 s59, 12
	s_waitcnt vmcnt(7)
	ds_write_b128 v228, v[0:3]
	s_waitcnt vmcnt(6)
	ds_write_b128 v228, v[4:7] offset:1024
	s_waitcnt vmcnt(5)
	ds_write_b128 v228, v[8:11] offset:2048
	s_waitcnt vmcnt(4)
	ds_write_b128 v228, v[12:15] offset:3072
	s_waitcnt vmcnt(3)
	ds_write_b128 v228, v[16:19] offset:4096
	s_waitcnt vmcnt(2)
	ds_write_b128 v228, v[20:23] offset:5120
	s_waitcnt vmcnt(1)
	ds_write_b128 v228, v[24:27] offset:6144
	s_waitcnt vmcnt(0)
; template <int NT>
; __device__ void attn_unitN(const P& p, int u) {
;     ...
; #pragma unroll
;     for (int dt = 0; dt < 4; ++dt) o[t][dt] = f32x4{0.f, 0.f, 0.f, 0.f};
;     mrun[t] = -1e30f; lrun[t] = 0.f;
;   }
;   const u16* kbase = Kd + (size_t)seq0 * 512 + h * 64 + quad * 16;
;   const u16* vbase = VdT + (size_t)seq0 * 512 + (size_t)h * 16 * 64 * L16;
;   KVB bA = attn_load_e<NT>(0, kbase, vbase, L16, rb, i0, lane);
;   KVB bB = attn_load_e<NT>(1, kbase, vbase, L16, rb, i0, lane);
	ds_write_b128 v228, v[28:31] offset:7168
	v_lshlrev_b32_e32 v2, 4, v35
	v_or_b32_e32 v0, v2, v239
	v_lshrrev_b32_e32 v243, 8, v0
	v_and_b32_e32 v244, 15, v0
	v_lshlrev_b32_e32 v243, 18, v243
	v_lshl_or_b32 v243, v244, 11, v243
	v_bfe_u32 v244, v0, 6, 2
	v_lshl_or_b32 v243, v244, 9, v243
	v_bfe_u32 v244, v0, 4, 2
	v_lshl_or_b32 v144, v244, 5, v243
	v_lshl_add_u64 v[0:1], v[154:155], 0, v[144:145]
	v_lshlrev_b32_e32 v144, s44, v238
	global_load_dwordx4 v[124:127], v[32:33], off
	global_load_dwordx4 v[120:123], v[32:33], off offset:16
	global_load_dwordx4 v[116:119], v[0:1], off
	global_load_dwordx4 v[112:115], v[0:1], off offset:16
	v_lshl_add_u64 v[0:1], s[4:5], 0, v[144:145]
	v_lshlrev_b64 v[0:1], 9, v[0:1]
	v_lshl_add_u64 v[0:1], s[0:1], 0, v[0:1]
	v_lshlrev_b32_e32 v144, 3, v34
	v_lshl_add_u64 v[0:1], v[0:1], 0, v[144:145]
	v_or_b32_e32 v3, 4, v239
	global_load_dwordx2 v[64:65], v[0:1], off
	global_load_dwordx2 v[68:69], v[0:1], off offset:128
	global_load_dwordx2 v[72:73], v[0:1], off offset:256
	global_load_dwordx2 v[76:77], v[0:1], off offset:384
	global_load_dwordx2 v[66:67], v[0:1], off offset:512
	global_load_dwordx2 v[70:71], v[0:1], off offset:640
	global_load_dwordx2 v[74:75], v[0:1], off offset:768
	global_load_dwordx2 v[78:79], v[0:1], off offset:896
	v_or_b32_e32 v0, v36, v3
	v_lshrrev_b32_e32 v243, 8, v0
	v_and_b32_e32 v244, 15, v0
	v_lshlrev_b32_e32 v243, 18, v243
	v_lshl_or_b32 v243, v244, 11, v243
	v_bfe_u32 v244, v0, 6, 2
	v_lshl_or_b32 v243, v244, 9, v243
	v_bfe_u32 v244, v0, 4, 2
	v_lshl_or_b32 v0, v244, 5, v243
	v_mov_b32_e32 v1, v145
	v_or_b32_e32 v2, v2, v3
	v_lshl_add_u64 v[0:1], v[154:155], 0, v[0:1]
	v_lshrrev_b32_e32 v243, 8, v2
	v_and_b32_e32 v244, 15, v2
	v_lshlrev_b32_e32 v243, 18, v243
	v_lshl_or_b32 v243, v244, 11, v243
	v_bfe_u32 v244, v2, 6, 2
	v_lshl_or_b32 v243, v244, 9, v243
	v_bfe_u32 v244, v2, 4, 2
	v_lshl_or_b32 v2, v244, 5, v243
	v_mov_b32_e32 v3, v145
	v_lshl_add_u64 v[2:3], v[154:155], 0, v[2:3]
	global_load_dwordx4 v[108:111], v[0:1], off
	global_load_dwordx4 v[104:107], v[0:1], off offset:16
	global_load_dwordx4 v[100:103], v[2:3], off
	global_load_dwordx4 v[96:99], v[2:3], off offset:16
	v_or_b32_e32 v0, 4, v238
	v_lshlrev_b32_e32 v0, s44, v0
	v_mov_b32_e32 v1, v145
	v_lshl_add_u64 v[0:1], s[4:5], 0, v[0:1]
	v_lshlrev_b64 v[0:1], 9, v[0:1]
	v_lshl_add_u64 v[0:1], s[0:1], 0, v[0:1]
	v_lshl_add_u64 v[0:1], v[0:1], 0, v[144:145]
	global_load_dwordx2 v[80:81], v[0:1], off
	global_load_dwordx2 v[84:85], v[0:1], off offset:128
	global_load_dwordx2 v[88:89], v[0:1], off offset:256
	global_load_dwordx2 v[92:93], v[0:1], off offset:384
	global_load_dwordx2 v[82:83], v[0:1], off offset:512
	global_load_dwordx2 v[86:87], v[0:1], off offset:640
	global_load_dwordx2 v[90:91], v[0:1], off offset:768
	global_load_dwordx2 v[94:95], v[0:1], off offset:896
	v_lshl_add_u64 v[158:159], s[0:1], 0, v[144:145]
	s_and_b32 s0, s42, 3
	v_and_or_b32 v229, v224, 12, s0
	v_lshl_or_b32 v230, v238, 2, s0
	s_add_i32 s0, s46, 0xfffffd80
	v_add_u32_e32 v231, s0, v240
	v_add_u32_e32 v232, s0, v241
	v_mov_b32_e32 v236, 0xf149f2ca
	v_mov_b32_e32 v237, 0xf149f2ca
	v_mov_b32_e32 v143, 0xf149f2ca
	s_mov_b32 s60, 0
	v_mov_b32_e32 v0, v145
	v_mov_b32_e32 v1, v145
	v_mov_b32_e32 v2, v145
	v_mov_b32_e32 v3, v145
	v_mov_b32_e32 v4, v145
	v_mov_b32_e32 v5, v145
	v_mov_b32_e32 v6, v145
	v_mov_b32_e32 v7, v145
	v_mov_b32_e32 v8, v145
	v_mov_b32_e32 v9, v145
	v_mov_b32_e32 v10, v145
	v_mov_b32_e32 v11, v145
	v_mov_b32_e32 v16, v145
	v_mov_b32_e32 v17, v145
	v_mov_b32_e32 v18, v145
	v_mov_b32_e32 v19, v145
	v_mov_b32_e32 v12, v145
	v_mov_b32_e32 v13, v145
	v_mov_b32_e32 v14, v145
	v_mov_b32_e32 v15, v145
	v_mov_b32_e32 v20, v145
	v_mov_b32_e32 v21, v145
	v_mov_b32_e32 v22, v145
	v_mov_b32_e32 v23, v145
	v_mov_b32_e32 v24, v145
	v_mov_b32_e32 v25, v145
	v_mov_b32_e32 v26, v145
	v_mov_b32_e32 v27, v145
	v_mov_b32_e32 v32, v145
	v_mov_b32_e32 v33, v145
	v_mov_b32_e32 v34, v145
	v_mov_b32_e32 v35, v145
	v_mov_b32_e32 v28, v145
	v_mov_b32_e32 v29, v145
	v_mov_b32_e32 v30, v145
	v_mov_b32_e32 v31, v145
	v_mov_b32_e32 v36, v145
	v_mov_b32_e32 v37, v145
	v_mov_b32_e32 v38, v145
	v_mov_b32_e32 v39, v145
	v_mov_b32_e32 v40, v145
	v_mov_b32_e32 v41, v145
	v_mov_b32_e32 v42, v145
	v_mov_b32_e32 v43, v145
	v_mov_b32_e32 v48, v145
	v_mov_b32_e32 v49, v145
	v_mov_b32_e32 v50, v145
	v_mov_b32_e32 v51, v145
	v_mov_b32_e32 v44, v145
	v_mov_b32_e32 v45, v145
	v_mov_b32_e32 v46, v145
	v_mov_b32_e32 v47, v145
	v_mov_b32_e32 v52, v145
	v_mov_b32_e32 v53, v145
	v_mov_b32_e32 v54, v145
	v_mov_b32_e32 v55, v145
	v_mov_b32_e32 v56, v145
	v_mov_b32_e32 v57, v145
	v_mov_b32_e32 v58, v145
	v_mov_b32_e32 v59, v145
	v_mov_b32_e32 v60, v145
	v_mov_b32_e32 v61, v145
	v_mov_b32_e32 v62, v145
	v_mov_b32_e32 v63, v145
	v_mov_b32_e32 v156, v145
	v_mov_b32_e32 v157, v145
	v_mov_b32_e32 v160, v145
	v_mov_b32_e32 v161, v145
; __device__ __forceinline__ void attn_step(int ks, const KVB& b, int L16, int r, int i0, int iq, int lane,
;                                           const bf16x8* qs, f32x4 (&o)[4], float& mrun, float& lrun) {
;   asm volatile("" : "+v"(lane), "+v"(iq));
;   asm volatile("" : "+s"(r), "+s"(i0));
;   const int quad = lane >> 4;
;   bf16x8 qB0 = qs[0], qB1 = qs[64];
;   int cV, sV; attn_desc(ks, quad, r, i0, cV, sV);
;   int D = ks < 12 ? 4 : (ks < 18 ? 16 : 64);
;   f32x4 z = {0.f, 0.f, 0.f, 0.f};
;   f32x4 sa = __builtin_amdgcn_mfma_f32_16x16x32_bf16(b.k0, qB0, z, 0, 0, 0);
;   sa = __builtin_amdgcn_mfma_f32_16x16x32_bf16(b.k1, qB1, sa, 0, 0, 0);
;   f32x4 sb = __builtin_amdgcn_mfma_f32_16x16x32_bf16(b.k2, qB0, z, 0, 0, 0);
;   sb = __builtin_amdgcn_mfma_f32_16x16x32_bf16(b.k3, qB1, sb, 0, 0, 0);
;   int jlo = max(iq - D + (cV < r ? 1 : 0), 0) - sV;
;   int jhi = min(iq + D - (cV > r ? 1 : 0), L16 - 1) - sV;
;   const float NINF = -__builtin_inff();
;   float s8[8];
;   float mt = -1e30f;
; #pragma unroll
;   for (int j = 0; j < 8; ++j) {
;     float sv = j < 4 ? sa[j] : sb[j - 4];
;     sv = (j >= jlo && j <= jhi) ? sv : NINF;
;     s8[j] = sv;
;     mt = fmaxf(mt, sv);
;   }
;   mt = fmaxf(mt, __shfl_xor(mt, 16));
;   mt = fmaxf(mt, __shfl_xor(mt, 32));
;   float mnew = fmaxf(mrun, mt);
;   float alpha = __builtin_amdgcn_exp2f(mrun - mnew);
;   mrun = mnew;
;   float ps = 0.f;
;   float p8[8];
; #pragma unroll
;   for (int j = 0; j < 8; ++j) { p8[j] = __builtin_amdgcn_exp2f(s8[j] - mnew); ps += p8[j]; }
;   lrun = lrun * alpha + ps;
.LBB0_232:
	s_mov_b32 s22, s42
	s_mov_b32 s23, s46
	ds_read_b128 v[128:131], v228
	s_add_i32 s0, s59, -12
	s_and_b32 s20, s0, 8
	s_add_i32 s0, s58, -4
	s_and_b32 s63, s0, 24
	s_add_i32 s63, s63, -4
	ds_read_b128 v[132:135], v228 offset:1024
	s_cmp_lt_u32 s60, 12
	s_waitcnt vmcnt(23) lgkmcnt(1)
	v_mfma_f32_16x16x32_bf16 v[136:139], v[124:127], v[128:131], 0
	v_add_u32_e32 v142, s20, v246
	s_cselect_b64 s[0:1], -1, 0
	s_waitcnt vmcnt(21)
	v_mfma_f32_16x16x32_bf16 v[128:131], v[116:119], v[128:131], 0
	v_and_or_b32 v141, s22, 3, v247
	s_and_b64 s[4:5], s[0:1], exec
	v_cndmask_b32_e64 v141, v141, v142, s[0:1]
	s_cselect_b32 s64, -4, -16
	s_cselect_b32 s61, 4, 16
	s_waitcnt lgkmcnt(0)
	v_mfma_f32_16x16x32_bf16 v[136:139], v[120:123], v[132:135], v[136:139]
	v_mov_b32_e32 v144, s64
	v_cmp_gt_i32_e32 vcc, s22, v141
	v_cmp_lt_i32_e64 s[4:5], s22, v141
	s_waitcnt vmcnt(20)
	v_mfma_f32_16x16x32_bf16 v[128:131], v[112:115], v[132:135], v[128:131]
	v_add_u32_e32 v133, s61, v225
	s_cselect_b32 s21, s63, s57
	v_addc_co_u32_e32 v132, vcc, v225, v144, vcc
	v_subbrev_co_u32_e64 v133, s[4:5], 0, v133, s[4:5]
	s_add_i32 s23, s23, s21
	v_max_i32_e32 v132, 0, v132
	v_min_i32_e32 v133, s43, v133
	v_subrev_u32_e32 v132, s23, v132
	v_subrev_u32_e32 v133, s23, v133
	v_cmp_lt_i32_e32 vcc, 0, v132
	v_cmp_gt_i32_e64 s[4:5], 0, v133
	s_or_b64 vcc, vcc, s[4:5]
	v_cndmask_b32_e32 v134, v136, v219, vcc
	v_cmp_lt_i32_e32 vcc, 1, v132
	v_cmp_gt_i32_e64 s[4:5], 1, v133
	s_or_b64 vcc, vcc, s[4:5]
	v_cndmask_b32_e32 v135, v137, v219, vcc
	v_cmp_lt_i32_e32 vcc, 2, v132
	v_cmp_gt_i32_e64 s[4:5], 2, v133
	s_or_b64 vcc, vcc, s[4:5]
	v_cndmask_b32_e32 v140, v138, v219, vcc
	v_cmp_lt_i32_e32 vcc, 3, v132
	v_cmp_gt_i32_e64 s[4:5], 3, v133
	s_or_b64 vcc, vcc, s[4:5]
	v_cndmask_b32_e32 v166, v139, v219, vcc
	v_cmp_lt_i32_e32 vcc, 4, v132
	v_cmp_gt_i32_e64 s[4:5], 4, v133
	s_or_b64 vcc, vcc, s[4:5]
	v_cndmask_b32_e32 v128, v128, v219, vcc
	v_cmp_lt_i32_e32 vcc, 5, v132
	v_cmp_gt_i32_e64 s[4:5], 5, v133
	s_or_b64 vcc, vcc, s[4:5]
	v_cndmask_b32_e32 v167, v129, v219, vcc
	v_cmp_lt_i32_e32 vcc, 6, v132
	v_cmp_gt_i32_e64 s[4:5], 6, v133
	s_or_b64 vcc, vcc, s[4:5]
	v_cndmask_b32_e32 v130, v130, v219, vcc
	v_cmp_lt_i32_e32 vcc, 7, v132
	v_cmp_gt_i32_e64 s[4:5], 7, v133
	s_or_b64 vcc, vcc, s[4:5]
	v_and_b32_e32 v133, 64, v199
	v_max3_f32 v136, v134, s41, v135
	v_cndmask_b32_e32 v132, v131, v219, vcc
	v_xor_b32_e32 v131, 16, v199
	v_add_u32_e32 v133, 64, v133
	v_max3_f32 v136, v136, v140, v166
	v_cmp_lt_i32_e32 vcc, v131, v133
	v_max3_f32 v129, v136, v128, v167
	v_max3_f32 v129, v129, v130, v132
	v_cndmask_b32_e32 v131, v199, v131, vcc
	v_lshlrev_b32_e32 v233, 2, v131
	v_mov_b32_e32 v131, v129
	s_nop 1
	v_permlane16_swap_b32_e32 v129, v131
	s_mov_b32 s4, s56
	s_mov_b32 s5, s46
	s_waitcnt lgkmcnt(0)
	v_max_f32_e32 v129, v129, v131
	v_xor_b32_e32 v131, 32, v199
	v_cmp_lt_i32_e32 vcc, v131, v133
	v_mov_b32_e32 v185, v226
	v_mov_b32_e32 v186, v225
	v_cndmask_b32_e32 v131, v199, v131, vcc
	v_lshlrev_b32_e32 v234, 2, v131
	v_mov_b32_e32 v131, v129
	s_nop 1
	v_permlane32_swap_b32_e32 v129, v131
	s_add_i32 s62, s60, 2
	s_mov_b64 s[24:25], -1
	s_waitcnt lgkmcnt(0)
	v_max3_f32 v183, v143, v129, v131
	v_sub_f32_e32 v129, v134, v183
	ds_read_b128 v[136:139], v228 offset:2048
	v_sub_f32_e32 v168, v143, v183
	v_sub_f32_e32 v133, v140, v183
	ds_read_b128 v[140:143], v228 offset:3072
	s_waitcnt lgkmcnt(1)
	v_mfma_f32_16x16x32_bf16 v[162:165], v[124:127], v[136:139], 0
	v_sub_f32_e32 v131, v135, v183
	v_sub_f32_e32 v135, v166, v183
	v_mfma_f32_16x16x32_bf16 v[136:139], v[116:119], v[136:139], 0
	v_add_u32_e32 v166, s20, v246
	v_and_or_b32 v134, s4, 3, v247
	v_cndmask_b32_e64 v134, v134, v166, s[0:1]
	s_waitcnt lgkmcnt(0)
	v_mfma_f32_16x16x32_bf16 v[162:165], v[120:123], v[140:143], v[162:165]
	s_add_i32 s22, s5, s21
	v_cmp_gt_i32_e32 vcc, s4, v134
	v_cmp_lt_i32_e64 s[4:5], s4, v134
	v_mfma_f32_16x16x32_bf16 v[136:139], v[112:115], v[140:143], v[136:139]
	v_add_u32_e32 v141, s61, v225
	v_addc_co_u32_e32 v140, vcc, v225, v144, vcc
	v_subbrev_co_u32_e64 v134, s[4:5], 0, v141, s[4:5]
	v_max_i32_e32 v140, 0, v140
	v_min_i32_e32 v134, s43, v134
	v_subrev_u32_e32 v140, s22, v140
	v_subrev_u32_e32 v134, s22, v134
	v_cmp_lt_i32_e32 vcc, 0, v140
	v_cmp_gt_i32_e64 s[4:5], 0, v134
	s_or_b64 vcc, vcc, s[4:5]
	v_cndmask_b32_e32 v143, v162, v219, vcc
	v_cmp_lt_i32_e32 vcc, 1, v140
	v_cmp_gt_i32_e64 s[4:5], 1, v134
	s_or_b64 vcc, vcc, s[4:5]
	v_cndmask_b32_e32 v162, v163, v219, vcc
	v_cmp_lt_i32_e32 vcc, 2, v140
	v_cmp_gt_i32_e64 s[4:5], 2, v134
	s_or_b64 vcc, vcc, s[4:5]
	v_cndmask_b32_e32 v164, v164, v219, vcc
	v_cmp_lt_i32_e32 vcc, 3, v140
	v_cmp_gt_i32_e64 s[4:5], 3, v134
	s_or_b64 vcc, vcc, s[4:5]
	v_cndmask_b32_e32 v166, v165, v219, vcc
	v_cmp_lt_i32_e32 vcc, 4, v140
	v_cmp_gt_i32_e64 s[4:5], 4, v134
	s_or_b64 vcc, vcc, s[4:5]
	v_cndmask_b32_e32 v136, v136, v219, vcc
	v_cmp_lt_i32_e32 vcc, 5, v140
	v_cmp_gt_i32_e64 s[4:5], 5, v134
	s_or_b64 vcc, vcc, s[4:5]
	v_cndmask_b32_e32 v169, v137, v219, vcc
	v_cmp_lt_i32_e32 vcc, 6, v140
	v_cmp_gt_i32_e64 s[4:5], 6, v134
	s_or_b64 vcc, vcc, s[4:5]
	v_max3_f32 v141, v143, s41, v162
	v_cndmask_b32_e32 v170, v138, v219, vcc
	v_cmp_lt_i32_e32 vcc, 7, v140
	v_cmp_gt_i32_e64 s[4:5], 7, v134
	v_max3_f32 v141, v141, v164, v166
	s_or_b64 vcc, vcc, s[4:5]
	v_max3_f32 v137, v141, v136, v169
	v_cndmask_b32_e32 v171, v139, v219, vcc
	v_max3_f32 v134, v137, v170, v171
	v_mov_b32_e32 v138, v134
	s_nop 1
	v_permlane16_swap_b32_e32 v134, v138
	v_sub_f32_e32 v128, v128, v183
	v_exp_f32_e32 v137, v128
	v_sub_f32_e32 v128, v167, v183
	v_exp_f32_e32 v139, v128
	v_sub_f32_e32 v128, v130, v183
	s_waitcnt lgkmcnt(0)
; __device__ __forceinline__ void attn_step(int ks, const KVB& b, int L16, int r, int i0, int iq, int lane,
;                                           const bf16x8* qs, f32x4 (&o)[4], float& mrun, float& lrun) {
;   asm volatile("" : "+v"(lane), "+v"(iq));
;   asm volatile("" : "+s"(r), "+s"(i0));
;   const int quad = lane >> 4;
;   bf16x8 qB0 = qs[0], qB1 = qs[64];
;   int cV, sV; attn_desc(ks, quad, r, i0, cV, sV);
;   int D = ks < 12 ? 4 : (ks < 18 ? 16 : 64);
;   f32x4 z = {0.f, 0.f, 0.f, 0.f};
;   f32x4 sa = __builtin_amdgcn_mfma_f32_16x16x32_bf16(b.k0, qB0, z, 0, 0, 0);
;   sa = __builtin_amdgcn_mfma_f32_16x16x32_bf16(b.k1, qB1, sa, 0, 0, 0);
;   f32x4 sb = __builtin_amdgcn_mfma_f32_16x16x32_bf16(b.k2, qB0, z, 0, 0, 0);
;   sb = __builtin_amdgcn_mfma_f32_16x16x32_bf16(b.k3, qB1, sb, 0, 0, 0);
;   int jlo = max(iq - D + (cV < r ? 1 : 0), 0) - sV;
;   int jhi = min(iq + D - (cV > r ? 1 : 0), L16 - 1) - sV;
;   const float NINF = -__builtin_inff();
;   float s8[8];
;   float mt = -1e30f;
; #pragma unroll
;   for (int j = 0; j < 8; ++j) {
;     float sv = j < 4 ? sa[j] : sb[j - 4];
;     sv = (j >= jlo && j <= jhi) ? sv : NINF;
;     s8[j] = sv;
;     mt = fmaxf(mt, sv);
;   }
;   mt = fmaxf(mt, __shfl_xor(mt, 16));
;   mt = fmaxf(mt, __shfl_xor(mt, 32));
;   float mnew = fmaxf(mrun, mt);
;   float alpha = __builtin_amdgcn_exp2f(mrun - mnew);
;   mrun = mnew;
;   float ps = 0.f;
;   float p8[8];
; #pragma unroll
;   for (int j = 0; j < 8; ++j) { p8[j] = __builtin_amdgcn_exp2f(s8[j] - mnew); ps += p8[j]; }
;   lrun = lrun * alpha + ps;
;   union { uint4 u; bf16x8 v; } pb;
;   pb.u = make_uint4(pack2(p8[0], p8[1]), pack2(p8[2], p8[3]), pack2(p8[4], p8[5]), pack2(p8[6], p8[7]));
; #pragma unroll
;   for (int dt = 0; dt < 4; ++dt) { o[dt][0] *= alpha; o[dt][1] *= alpha; o[dt][2] *= alpha; o[dt][3] *= alpha; }
;   o[0] = __builtin_amdgcn_mfma_f32_16x16x32_bf16(b.v0, pb.v, o[0], 0, 0, 0);
;   o[1] = __builtin_amdgcn_mfma_f32_16x16x32_bf16(b.v1, pb.v, o[1], 0, 0, 0);
;   o[2] = __builtin_amdgcn_mfma_f32_16x16x32_bf16(b.v2, pb.v, o[2], 0, 0, 0);
;   o[3] = __builtin_amdgcn_mfma_f32_16x16x32_bf16(b.v3, pb.v, o[3], 0, 0, 0);
	v_max_f32_e32 v130, v138, v138
	v_max_f32_e32 v130, v134, v130
	v_mov_b32_e32 v134, v130
	s_nop 1
	v_permlane32_swap_b32_e32 v130, v134
	v_exp_f32_e32 v142, v168
	v_exp_f32_e32 v141, v128
	v_sub_f32_e32 v128, v132, v183
	v_exp_f32_e32 v163, v128
	s_waitcnt lgkmcnt(0)
	v_max3_f32 v165, v237, v130, v134
	v_sub_f32_e32 v128, v143, v165
	v_pk_mul_f32 v[62:63], v[62:63], v[142:143] op_sel_hi:[1,0]
	v_pk_mul_f32 v[60:61], v[60:61], v[142:143] op_sel_hi:[1,0]
	v_sub_f32_e32 v143, v171, v165
	v_sub_f32_e32 v172, v237, v165
	v_sub_f32_e32 v130, v162, v165
	v_pk_mul_f32 v[58:59], v[58:59], v[142:143] op_sel_hi:[1,0]
	v_pk_mul_f32 v[56:57], v[56:57], v[142:143] op_sel_hi:[1,0]
	v_exp_f32_e32 v162, v143
	v_pk_mul_f32 v[54:55], v[54:55], v[142:143] op_sel_hi:[1,0]
	v_pk_mul_f32 v[52:53], v[52:53], v[142:143] op_sel_hi:[1,0]
	v_pk_mul_f32 v[46:47], v[46:47], v[142:143] op_sel_hi:[1,0]
	v_pk_mul_f32 v[44:45], v[44:45], v[142:143] op_sel_hi:[1,0]
	s_mov_b32 s4, s8
	s_mov_b32 s5, s46
	v_sub_f32_e32 v132, v164, v165
	v_sub_f32_e32 v140, v170, v165
	v_exp_f32_e32 v164, v172
	ds_read_b128 v[170:173], v228 offset:4096
	ds_read_b128 v[174:177], v228 offset:5120
	s_waitcnt lgkmcnt(1)
	v_mfma_f32_16x16x32_bf16 v[178:181], v[124:127], v[170:173], 0
	v_add_u32_e32 v184, s20, v246
	v_mfma_f32_16x16x32_bf16 v[170:173], v[116:119], v[170:173], 0
	v_and_or_b32 v143, s4, 3, v247
	v_cndmask_b32_e64 v143, v143, v184, s[0:1]
	s_add_i32 s22, s5, s21
	s_waitcnt lgkmcnt(0)
	v_mfma_f32_16x16x32_bf16 v[178:181], v[120:123], v[174:177], v[178:181]
	v_cmp_gt_i32_e32 vcc, s4, v143
	v_cmp_lt_i32_e64 s[4:5], s4, v143
	v_exp_f32_e32 v129, v129
	v_mfma_f32_16x16x32_bf16 v[170:173], v[112:115], v[174:177], v[170:173]
	v_add_u32_e32 v175, s61, v225
	v_addc_co_u32_e32 v174, vcc, v225, v144, vcc
	v_subbrev_co_u32_e64 v143, s[4:5], 0, v175, s[4:5]
	v_max_i32_e32 v174, 0, v174
	v_min_i32_e32 v143, s43, v143
	v_subrev_u32_e32 v174, s22, v174
	v_subrev_u32_e32 v143, s22, v143
	v_cmp_lt_i32_e32 vcc, 0, v174
	v_cmp_gt_i32_e64 s[4:5], 0, v143
	s_or_b64 vcc, vcc, s[4:5]
	v_cndmask_b32_e32 v175, v178, v219, vcc
	v_cmp_lt_i32_e32 vcc, 1, v174
	v_cmp_gt_i32_e64 s[4:5], 1, v143
	s_or_b64 vcc, vcc, s[4:5]
	v_cndmask_b32_e32 v176, v179, v219, vcc
	v_cmp_lt_i32_e32 vcc, 2, v174
	v_cmp_gt_i32_e64 s[4:5], 2, v143
	s_or_b64 vcc, vcc, s[4:5]
	v_cndmask_b32_e32 v178, v180, v219, vcc
	v_cmp_lt_i32_e32 vcc, 3, v174
	v_cmp_gt_i32_e64 s[4:5], 3, v143
	s_or_b64 vcc, vcc, s[4:5]
	v_cndmask_b32_e32 v182, v181, v219, vcc
	v_cmp_lt_i32_e32 vcc, 4, v174
	v_cmp_gt_i32_e64 s[4:5], 4, v143
	s_or_b64 vcc, vcc, s[4:5]
	v_cndmask_b32_e32 v170, v170, v219, vcc
	v_cmp_lt_i32_e32 vcc, 5, v174
	v_cmp_gt_i32_e64 s[4:5], 5, v143
	s_or_b64 vcc, vcc, s[4:5]
	v_cndmask_b32_e32 v184, v171, v219, vcc
	v_cmp_lt_i32_e32 vcc, 6, v174
	v_cmp_gt_i32_e64 s[4:5], 6, v143
	s_or_b64 vcc, vcc, s[4:5]
	v_max3_f32 v177, v175, s41, v176
	v_cndmask_b32_e32 v172, v172, v219, vcc
	v_cmp_lt_i32_e32 vcc, 7, v174
	v_cmp_gt_i32_e64 s[4:5], 7, v143
	v_max3_f32 v177, v177, v178, v182
	s_or_b64 vcc, vcc, s[4:5]
	v_max3_f32 v171, v177, v170, v184
	v_cndmask_b32_e32 v143, v173, v219, vcc
	v_max3_f32 v171, v171, v172, v143
	v_mov_b32_e32 v173, v171
	s_nop 1
	v_permlane16_swap_b32_e32 v171, v173
	v_exp_f32_e32 v131, v131
	v_exp_f32_e32 v133, v133
	v_exp_f32_e32 v135, v135
	v_sub_f32_e32 v134, v166, v165
	s_waitcnt lgkmcnt(0)
	v_max_f32_e32 v171, v171, v173
	v_sub_f32_e32 v136, v136, v165
	v_sub_f32_e32 v138, v169, v165
	v_mov_b32_e32 v173, v171
	s_nop 1
	v_permlane32_swap_b32_e32 v171, v173
	v_exp_f32_e32 v128, v128
	v_exp_f32_e32 v130, v130
	v_exp_f32_e32 v132, v132
	v_exp_f32_e32 v134, v134
	v_exp_f32_e32 v136, v136
	v_exp_f32_e32 v138, v138
	v_exp_f32_e32 v140, v140
	v_cvt_pk_bf16_f32 v166, v129, v131
	v_cvt_pk_bf16_f32 v167, v133, v135
	v_cvt_pk_bf16_f32 v168, v137, v139
	v_cvt_pk_bf16_f32 v169, v141, v163
	v_pk_mul_f32 v[50:51], v[50:51], v[164:165] op_sel_hi:[1,0]
	v_pk_mul_f32 v[48:49], v[48:49], v[164:165] op_sel_hi:[1,0]
	s_waitcnt vmcnt(15)
	v_mfma_f32_16x16x32_bf16 v[60:63], v[64:67], v[166:169], v[60:63]
	v_mul_f32_e64 v42, v42, v164
	v_mul_f32_e64 v43, v43, v164
	v_pk_mul_f32 v[40:41], v[40:41], v[164:165] op_sel_hi:[1,0]
	v_pk_mul_f32 v[38:39], v[38:39], v[164:165] op_sel_hi:[1,0]
	s_waitcnt vmcnt(14)
	v_mfma_f32_16x16x32_bf16 v[56:59], v[68:71], v[166:169], v[56:59]
	v_mul_f32_e64 v36, v36, v164
	v_mul_f32_e64 v37, v37, v164
	v_pk_mul_f32 v[30:31], v[30:31], v[164:165] op_sel_hi:[1,0]
	v_pk_mul_f32 v[28:29], v[28:29], v[164:165] op_sel_hi:[1,0]
	s_waitcnt vmcnt(13)
	v_mfma_f32_16x16x32_bf16 v[52:55], v[72:75], v[166:169], v[52:55]
	s_waitcnt lgkmcnt(0)
	v_max3_f32 v204, v236, v171, v173
	s_mov_b32 s4, s10
	s_mov_b32 s5, s46
	s_waitcnt vmcnt(12)
	v_mfma_f32_16x16x32_bf16 v[44:47], v[76:79], v[166:169], v[44:47]
	v_cvt_pk_bf16_f32 v166, v128, v130
	v_cvt_pk_bf16_f32 v167, v132, v134
	v_cvt_pk_bf16_f32 v168, v136, v138
	v_cvt_pk_bf16_f32 v169, v140, v162
	s_nop 1
	v_mfma_f32_16x16x32_bf16 v[48:51], v[64:67], v[166:169], v[48:51]
	v_mfma_f32_16x16x32_bf16 v[40:43], v[68:71], v[166:169], v[40:43]
	v_mfma_f32_16x16x32_bf16 v[36:39], v[72:75], v[166:169], v[36:39]
	v_mfma_f32_16x16x32_bf16 v[28:31], v[76:79], v[166:169], v[28:31]
	v_sub_f32_e32 v167, v175, v204
	v_sub_f32_e32 v168, v176, v204
	ds_read_b128 v[174:177], v228 offset:6144
	v_exp_f32_e32 v169, v168
	v_sub_f32_e32 v168, v178, v204
	ds_read_b128 v[178:181], v228 offset:7168
	s_waitcnt lgkmcnt(1)
; __device__ __forceinline__ void attn_step(int ks, const KVB& b, int L16, int r, int i0, int iq, int lane,
;                                           const bf16x8* qs, f32x4 (&o)[4], float& mrun, float& lrun) {
;     ...
;   f32x4 sa = __builtin_amdgcn_mfma_f32_16x16x32_bf16(b.k0, qB0, z, 0, 0, 0);
;   sa = __builtin_amdgcn_mfma_f32_16x16x32_bf16(b.k1, qB1, sa, 0, 0, 0);
;   f32x4 sb = __builtin_amdgcn_mfma_f32_16x16x32_bf16(b.k2, qB0, z, 0, 0, 0);
;   sb = __builtin_amdgcn_mfma_f32_16x16x32_bf16(b.k3, qB1, sb, 0, 0, 0);
;   int jlo = max(iq - D + (cV < r ? 1 : 0), 0) - sV;
;   int jhi = min(iq + D - (cV > r ? 1 : 0), L16 - 1) - sV;
;   const float NINF = -__builtin_inff();
;   float s8[8];
;   float mt = -1e30f;
; #pragma unroll
;   for (int j = 0; j < 8; ++j) {
;     float sv = j < 4 ? sa[j] : sb[j - 4];
;     sv = (j >= jlo && j <= jhi) ? sv : NINF;
;     s8[j] = sv;
;     mt = fmaxf(mt, sv);
;   }
;   mt = fmaxf(mt, __shfl_xor(mt, 16));
;   mt = fmaxf(mt, __shfl_xor(mt, 32));
;   float mnew = fmaxf(mrun, mt);
;   float alpha = __builtin_amdgcn_exp2f(mrun - mnew);
;   mrun = mnew;
;   float ps = 0.f;
;   float p8[8];
; #pragma unroll
;   for (int j = 0; j < 8; ++j) { p8[j] = __builtin_amdgcn_exp2f(s8[j] - mnew); ps += p8[j]; }
;   lrun = lrun * alpha + ps;
;   union { uint4 u; bf16x8 v; } pb;
;   pb.u = make_uint4(pack2(p8[0], p8[1]), pack2(p8[2], p8[3]), pack2(p8[4], p8[5]), pack2(p8[6], p8[7]));
; #pragma unroll
;   for (int dt = 0; dt < 4; ++dt) { o[dt][0] *= alpha; o[dt][1] *= alpha; o[dt][2] *= alpha; o[dt][3] *= alpha; }
;   o[0] = __builtin_amdgcn_mfma_f32_16x16x32_bf16(b.v0, pb.v, o[0], 0, 0, 0);
;   o[1] = __builtin_amdgcn_mfma_f32_16x16x32_bf16(b.v1, pb.v, o[1], 0, 0, 0);
;   o[2] = __builtin_amdgcn_mfma_f32_16x16x32_bf16(b.v2, pb.v, o[2], 0, 0, 0);
;   o[3] = __builtin_amdgcn_mfma_f32_16x16x32_bf16(b.v3, pb.v, o[3], 0, 0, 0);
; template <int NT>
; __device__ void attn_unitN(const P& p, int u) {
;     ...
;     bA = attn_load_e<NT>(ks + 2, kbase, vbase, L16, rb, i0, lane);
	v_mfma_f32_16x16x32_bf16 v[124:127], v[124:127], v[174:177], 0
	v_sub_f32_e32 v166, v236, v204
	v_exp_f32_e32 v171, v168
	v_sub_f32_e32 v168, v182, v204
	s_waitcnt lgkmcnt(0)
	v_mfma_f32_16x16x32_bf16 v[120:123], v[120:123], v[178:181], v[124:127]
	v_exp_f32_e32 v173, v168
	v_sub_f32_e32 v168, v170, v204
	v_exp_f32_e32 v167, v167
	v_ashrrev_i32_e32 v124, 4, v185
	v_mfma_f32_16x16x32_bf16 v[116:119], v[116:119], v[174:177], 0
	v_add_u32_e32 v125, s20, v124
	v_lshlrev_b32_e32 v124, 2, v124
	v_and_or_b32 v124, s4, 3, v124
	v_cndmask_b32_e64 v124, v124, v125, s[0:1]
	s_add_i32 s20, s5, s21
	v_mfma_f32_16x16x32_bf16 v[112:115], v[112:115], v[178:181], v[116:119]
	v_cmp_gt_i32_e32 vcc, s4, v124
	v_cmp_lt_i32_e64 s[4:5], s4, v124
	v_exp_f32_e32 v175, v168
	v_add_u32_e32 v117, s61, v186
	v_addc_co_u32_e32 v116, vcc, v186, v144, vcc
	v_subbrev_co_u32_e64 v117, s[4:5], 0, v117, s[4:5]
	v_max_i32_e32 v116, 0, v116
	v_min_i32_e32 v117, s43, v117
	v_subrev_u32_e32 v116, s20, v116
	v_subrev_u32_e32 v117, s20, v117
	v_cmp_lt_i32_e32 vcc, 0, v116
	v_cmp_gt_i32_e64 s[4:5], 0, v117
	s_or_b64 vcc, vcc, s[4:5]
	v_cndmask_b32_e32 v118, v120, v219, vcc
	v_cmp_lt_i32_e32 vcc, 1, v116
	v_cmp_gt_i32_e64 s[4:5], 1, v117
	s_or_b64 vcc, vcc, s[4:5]
	v_cndmask_b32_e32 v119, v121, v219, vcc
	v_cmp_lt_i32_e32 vcc, 2, v116
	v_cmp_gt_i32_e64 s[4:5], 2, v117
	s_or_b64 vcc, vcc, s[4:5]
	v_cndmask_b32_e32 v121, v122, v219, vcc
	v_cmp_lt_i32_e32 vcc, 3, v116
	v_cmp_gt_i32_e64 s[4:5], 3, v117
	s_or_b64 vcc, vcc, s[4:5]
	v_cndmask_b32_e32 v122, v123, v219, vcc
	v_cmp_lt_i32_e32 vcc, 4, v116
	v_cmp_gt_i32_e64 s[4:5], 4, v117
	s_or_b64 vcc, vcc, s[4:5]
	v_cndmask_b32_e32 v112, v112, v219, vcc
	v_cmp_lt_i32_e32 vcc, 5, v116
	v_cmp_gt_i32_e64 s[4:5], 5, v117
	s_or_b64 vcc, vcc, s[4:5]
	v_cndmask_b32_e32 v113, v113, v219, vcc
	v_cmp_lt_i32_e32 vcc, 6, v116
	v_cmp_gt_i32_e64 s[4:5], 6, v117
	s_or_b64 vcc, vcc, s[4:5]
	v_max3_f32 v120, v118, s41, v119
	v_cndmask_b32_e32 v114, v114, v219, vcc
	v_cmp_lt_i32_e32 vcc, 7, v116
	v_cmp_gt_i32_e64 s[4:5], 7, v117
	v_max3_f32 v120, v120, v121, v122
	s_or_b64 vcc, vcc, s[4:5]
	v_max3_f32 v120, v120, v112, v113
	v_cndmask_b32_e32 v116, v115, v219, vcc
	v_max3_f32 v115, v120, v114, v116
	v_mov_b32_e32 v117, v115
	s_nop 1
	v_permlane16_swap_b32_e32 v115, v117
	v_sub_f32_e32 v120, v184, v204
	v_exp_f32_e32 v177, v120
	v_sub_f32_e32 v120, v172, v204
	v_exp_f32_e32 v144, v166
	s_waitcnt lgkmcnt(0)
	v_max_f32_e32 v115, v115, v117
	v_mov_b32_e32 v117, v115
	s_nop 1
	v_permlane32_swap_b32_e32 v115, v117
	v_exp_f32_e32 v179, v120
	v_sub_f32_e32 v120, v143, v204
	s_add_i32 s4, s59, -4
	v_exp_f32_e32 v181, v120
	s_waitcnt lgkmcnt(0)
	v_max3_f32 v203, v235, v115, v117
	v_sub_f32_e32 v115, v118, v203
	v_exp_f32_e32 v166, v115
	v_sub_f32_e32 v115, v119, v203
	v_sub_f32_e32 v112, v112, v203
	v_exp_f32_e32 v168, v115
	v_sub_f32_e32 v115, v121, v203
	v_exp_f32_e32 v174, v112
	v_sub_f32_e32 v112, v113, v203
	v_sub_f32_e32 v117, v235, v203
	v_exp_f32_e32 v170, v115
	v_sub_f32_e32 v115, v122, v203
	v_exp_f32_e32 v176, v112
	v_sub_f32_e32 v112, v114, v203
	v_sub_f32_e32 v116, v116, v203
	s_and_b32 s65, s4, 8
	v_exp_f32_e32 v172, v115
	v_exp_f32_e32 v178, v112
	v_exp_f32_e32 v180, v116
	v_exp_f32_e32 v182, v117
	s_xor_b32 s22, s65, 8
	s_cmp_gt_u32 s60, 15
	s_cselect_b64 s[20:21], -1, 0
	v_pk_mul_f32 v[34:35], v[34:35], v[144:145] op_sel_hi:[1,0]
	v_pk_mul_f32 v[32:33], v[32:33], v[144:145] op_sel_hi:[1,0]
	v_cvt_pk_bf16_f32 v112, v167, v169
	v_cvt_pk_bf16_f32 v113, v171, v173
	v_cvt_pk_bf16_f32 v114, v175, v177
	v_cvt_pk_bf16_f32 v115, v179, v181
	v_pk_mul_f32 v[26:27], v[26:27], v[144:145] op_sel_hi:[1,0]
	v_pk_mul_f32 v[24:25], v[24:25], v[144:145] op_sel_hi:[1,0]
	v_pk_mul_f32 v[22:23], v[22:23], v[144:145] op_sel_hi:[1,0]
	v_pk_mul_f32 v[20:21], v[20:21], v[144:145] op_sel_hi:[1,0]
	v_pk_mul_f32 v[14:15], v[14:15], v[144:145] op_sel_hi:[1,0]
	v_pk_mul_f32 v[12:13], v[12:13], v[144:145] op_sel_hi:[1,0]
	s_and_b64 s[4:5], s[20:21], exec
	v_mfma_f32_16x16x32_bf16 v[32:35], v[64:67], v[112:115], v[32:35]
	v_mul_f32_e64 v18, v18, v182
	v_mul_f32_e64 v19, v19, v182
	v_pk_mul_f32 v[16:17], v[16:17], v[182:183] op_sel_hi:[1,0]
	v_pk_mul_f32 v[10:11], v[10:11], v[182:183] op_sel_hi:[1,0]
	v_mfma_f32_16x16x32_bf16 v[24:27], v[68:71], v[112:115], v[24:27]
	v_mul_f32_e64 v8, v8, v182
	v_mul_f32_e64 v9, v9, v182
	v_pk_mul_f32 v[6:7], v[6:7], v[182:183] op_sel_hi:[1,0]
	v_pk_mul_f32 v[4:5], v[4:5], v[182:183] op_sel_hi:[1,0]
	v_mfma_f32_16x16x32_bf16 v[20:23], v[72:75], v[112:115], v[20:23]
	v_mul_f32_e64 v2, v2, v182
	v_mul_f32_e64 v3, v3, v182
	v_pk_mul_f32 v[0:1], v[0:1], v[182:183] op_sel_hi:[1,0]
	s_cselect_b32 s66, s22, 0
	v_mfma_f32_16x16x32_bf16 v[12:15], v[76:79], v[112:115], v[12:15]
	v_cvt_pk_bf16_f32 v112, v166, v168
	v_cvt_pk_bf16_f32 v113, v170, v172
	v_cvt_pk_bf16_f32 v114, v174, v176
	v_cvt_pk_bf16_f32 v115, v178, v180
	s_add_i32 s66, s66, s42
	s_cmp_gt_u32 s60, 9
	v_mfma_f32_16x16x32_bf16 v[16:19], v[64:67], v[112:115], v[16:19]
	s_cselect_b64 s[22:23], -1, 0
	s_and_b64 vcc, exec, s[22:23]
	v_mfma_f32_16x16x32_bf16 v[8:11], v[68:71], v[112:115], v[8:11]
	v_mfma_f32_16x16x32_bf16 v[4:7], v[72:75], v[112:115], v[4:7]
	v_mfma_f32_16x16x32_bf16 v[0:3], v[76:79], v[112:115], v[0:3]
	s_cbranch_vccz .LBB0_238
	s_mov_b64 vcc, s[4:5]
	s_cbranch_vccz .LBB0_235
	v_lshl_add_u32 v64, s62, 5, v231
	s_mov_b64 s[24:25], 0

; __device__ __forceinline__ void attn_step(int ks, const KVB& b, int L16, int r, int i0, int iq, int lane,
;                                           const bf16x8* qs, f32x4 (&o)[4], float& mrun, float& lrun) {
;   asm volatile("" : "+v"(lane), "+v"(iq));
;   asm volatile("" : "+s"(r), "+s"(i0));
;   const int quad = lane >> 4;
;   bf16x8 qB0 = qs[0], qB1 = qs[64];
;   int cV, sV; attn_desc(ks, quad, r, i0, cV, sV);
;   int D = ks < 12 ? 4 : (ks < 18 ? 16 : 64);
;   f32x4 z = {0.f, 0.f, 0.f, 0.f};
;   f32x4 sa = __builtin_amdgcn_mfma_f32_16x16x32_bf16(b.k0, qB0, z, 0, 0, 0);
;   sa = __builtin_amdgcn_mfma_f32_16x16x32_bf16(b.k1, qB1, sa, 0, 0, 0);
;   f32x4 sb = __builtin_amdgcn_mfma_f32_16x16x32_bf16(b.k2, qB0, z, 0, 0, 0);
;   sb = __builtin_amdgcn_mfma_f32_16x16x32_bf16(b.k3, qB1, sb, 0, 0, 0);
;   int jlo = max(iq - D + (cV < r ? 1 : 0), 0) - sV;
;   int jhi = min(iq + D - (cV > r ? 1 : 0), L16 - 1) - sV;
;   const float NINF = -__builtin_inff();
;   float s8[8];
;   float mt = -1e30f;
; #pragma unroll
;   for (int j = 0; j < 8; ++j) {
;     float sv = j < 4 ? sa[j] : sb[j - 4];
;     sv = (j >= jlo && j <= jhi) ? sv : NINF;
;     s8[j] = sv;
;     mt = fmaxf(mt, sv);
;   }
;   mt = fmaxf(mt, __shfl_xor(mt, 16));
;   mt = fmaxf(mt, __shfl_xor(mt, 32));
;   float mnew = fmaxf(mrun, mt);
;   float alpha = __builtin_amdgcn_exp2f(mrun - mnew);
;   mrun = mnew;
;   float ps = 0.f;
;   float p8[8];
; #pragma unroll
;   for (int j = 0; j < 8; ++j) { p8[j] = __builtin_amdgcn_exp2f(s8[j] - mnew); ps += p8[j]; }
; template <int NT>
; __device__ void attn_unitN(const P& p, int u) {
;     ...
;     bA = attn_load_e<NT>(ks + 2, kbase, vbase, L16, rb, i0, lane);
; #pragma unroll
;     for (int t = 0; t < NT; ++t)
;       attn_step(ks + 1, bB, L16, rb + RS * t, i0, iq, lane, qs + t * 128, o[t], mrun[t], lrun[t]);
;     bB = attn_load_e<NT>(ks + 3, kbase, vbase, L16, rb, i0, lane);
.LBB0_248:
	v_ashrrev_i32_e32 v65, 31, v64
	v_ashrrev_i32_e32 v66, 2, v66
	v_lshlrev_b64 v[64:65], s44, v[64:65]
	v_ashrrev_i32_e32 v67, 31, v66
	v_lshl_add_u64 v[64:65], v[64:65], 0, v[66:67]
	v_lshlrev_b64 v[64:65], 9, v[64:65]
	v_lshl_add_u64 v[78:79], v[158:159], 0, v[64:65]
	s_mov_b32 s24, s42
	s_mov_b32 s25, s46
	global_load_dwordx2 v[64:65], v[78:79], off
	global_load_dwordx2 v[68:69], v[78:79], off offset:128
	global_load_dwordx2 v[72:73], v[78:79], off offset:256
	global_load_dwordx2 v[76:77], v[78:79], off offset:384
	global_load_dwordx2 v[66:67], v[78:79], off offset:512
	global_load_dwordx2 v[70:71], v[78:79], off offset:640
	global_load_dwordx2 v[74:75], v[78:79], off offset:768
	s_nop 0
	global_load_dwordx2 v[78:79], v[78:79], off offset:896
	ds_read_b128 v[184:187], v228
	ds_read_b128 v[188:191], v228 offset:1024
	s_add_i32 s4, s59, -8
	s_waitcnt vmcnt(23) lgkmcnt(1)
	v_mfma_f32_16x16x32_bf16 v[192:195], v[108:111], v[184:187], 0
	s_and_b32 s22, s4, 12
	v_add_u32_e32 v197, s22, v246
	s_waitcnt vmcnt(21)
	v_mfma_f32_16x16x32_bf16 v[184:187], v[100:103], v[184:187], 0
	s_add_i32 s23, s57, 8
	v_and_or_b32 v143, s24, 3, v247
	v_cndmask_b32_e64 v143, v143, v197, s[0:1]
	s_and_b64 s[4:5], s[0:1], exec
	s_waitcnt lgkmcnt(0)
	v_mfma_f32_16x16x32_bf16 v[192:195], v[104:107], v[188:191], v[192:195]
	v_mov_b32_e32 v218, s64
	v_cmp_gt_i32_e32 vcc, s24, v143
	v_cmp_lt_i32_e64 s[4:5], s24, v143
	s_waitcnt vmcnt(20)
	v_mfma_f32_16x16x32_bf16 v[184:187], v[96:99], v[188:191], v[184:187]
	v_add_u32_e32 v189, s61, v225
	s_cselect_b32 s23, s63, s23
	v_addc_co_u32_e32 v188, vcc, v225, v218, vcc
	v_subbrev_co_u32_e64 v143, s[4:5], 0, v189, s[4:5]
	s_add_i32 s25, s25, s23
	v_max_i32_e32 v188, 0, v188
	v_min_i32_e32 v143, s43, v143
	v_subrev_u32_e32 v188, s25, v188
	v_subrev_u32_e32 v143, s25, v143
	v_cmp_lt_i32_e32 vcc, 0, v188
	v_cmp_gt_i32_e64 s[4:5], 0, v143
	s_or_b64 vcc, vcc, s[4:5]
	v_cndmask_b32_e32 v189, v192, v219, vcc
	v_cmp_lt_i32_e32 vcc, 1, v188
	v_cmp_gt_i32_e64 s[4:5], 1, v143
	s_or_b64 vcc, vcc, s[4:5]
	v_cndmask_b32_e32 v190, v193, v219, vcc
	v_cmp_lt_i32_e32 vcc, 2, v188
	v_cmp_gt_i32_e64 s[4:5], 2, v143
	s_or_b64 vcc, vcc, s[4:5]
	v_cndmask_b32_e32 v196, v194, v219, vcc
	v_cmp_lt_i32_e32 vcc, 3, v188
	v_cmp_gt_i32_e64 s[4:5], 3, v143
	s_or_b64 vcc, vcc, s[4:5]
	v_cndmask_b32_e32 v197, v195, v219, vcc
	v_cmp_lt_i32_e32 vcc, 4, v188
	v_cmp_gt_i32_e64 s[4:5], 4, v143
	s_or_b64 vcc, vcc, s[4:5]
	v_cndmask_b32_e32 v184, v184, v219, vcc
	v_cmp_lt_i32_e32 vcc, 5, v188
	v_cmp_gt_i32_e64 s[4:5], 5, v143
	s_or_b64 vcc, vcc, s[4:5]
	v_cndmask_b32_e32 v198, v185, v219, vcc
	v_cmp_lt_i32_e32 vcc, 6, v188
	v_cmp_gt_i32_e64 s[4:5], 6, v143
	s_or_b64 vcc, vcc, s[4:5]
	v_max3_f32 v191, v189, s41, v190
	v_cndmask_b32_e32 v186, v186, v219, vcc
	v_cmp_lt_i32_e32 vcc, 7, v188
	v_cmp_gt_i32_e64 s[4:5], 7, v143
	v_max3_f32 v191, v191, v196, v197
	s_or_b64 vcc, vcc, s[4:5]
	v_max3_f32 v185, v191, v184, v198
	v_cndmask_b32_e32 v188, v187, v219, vcc
	v_max3_f32 v143, v185, v186, v188
	v_mov_b32_e32 v185, v143
	s_nop 1
	v_permlane16_swap_b32_e32 v143, v185
	s_mov_b32 s4, s56
	s_mov_b32 s5, s46
	s_waitcnt lgkmcnt(0)
	v_max_f32_e32 v143, v143, v185
	v_mov_b32_e32 v185, v143
	s_nop 1
	v_permlane32_swap_b32_e32 v143, v185
	s_waitcnt lgkmcnt(0)
	v_max3_f32 v143, v183, v143, v185
	v_sub_f32_e32 v187, v190, v143
	ds_read_b128 v[192:195], v228 offset:2048
	ds_read_b128 v[206:209], v228 offset:3072
	v_sub_f32_e32 v185, v189, v143
	v_sub_f32_e32 v189, v196, v143
	v_add_u32_e32 v196, s22, v246
	s_waitcnt lgkmcnt(1)
	v_mfma_f32_16x16x32_bf16 v[210:213], v[108:111], v[192:195], 0
	v_and_or_b32 v190, s4, 3, v247
	v_cndmask_b32_e64 v190, v190, v196, s[0:1]
	v_sub_f32_e32 v191, v197, v143
	s_add_i32 s24, s5, s23
	v_cmp_gt_i32_e32 vcc, s4, v190
	v_add_u32_e32 v197, s61, v225
	v_cmp_lt_i32_e64 s[4:5], s4, v190
	v_addc_co_u32_e32 v196, vcc, v225, v218, vcc
	s_nop 0
	v_subbrev_co_u32_e64 v190, s[4:5], 0, v197, s[4:5]
	s_waitcnt lgkmcnt(0)
	v_mfma_f32_16x16x32_bf16 v[210:213], v[104:107], v[206:209], v[210:213]
	v_max_i32_e32 v196, 0, v196
	v_min_i32_e32 v190, s43, v190
	v_subrev_u32_e32 v196, s24, v196
	v_subrev_u32_e32 v190, s24, v190
	v_cmp_lt_i32_e32 vcc, 0, v196
	v_cmp_gt_i32_e64 s[4:5], 0, v190
	s_or_b64 vcc, vcc, s[4:5]
	v_mfma_f32_16x16x32_bf16 v[192:195], v[100:103], v[192:195], 0
	v_cndmask_b32_e32 v200, v210, v219, vcc
	v_cmp_lt_i32_e32 vcc, 1, v196
	v_cmp_gt_i32_e64 s[4:5], 1, v190
	s_or_b64 vcc, vcc, s[4:5]
	v_cndmask_b32_e32 v202, v211, v219, vcc
	v_cmp_lt_i32_e32 vcc, 2, v196
	v_cmp_gt_i32_e64 s[4:5], 2, v190
	s_or_b64 vcc, vcc, s[4:5]
	v_mfma_f32_16x16x32_bf16 v[192:195], v[96:99], v[206:209], v[192:195]
	v_cndmask_b32_e32 v205, v212, v219, vcc
	v_cmp_lt_i32_e32 vcc, 3, v196
	v_cmp_gt_i32_e64 s[4:5], 3, v190
	s_or_b64 vcc, vcc, s[4:5]
	v_cndmask_b32_e32 v206, v213, v219, vcc
	v_cmp_lt_i32_e32 vcc, 4, v196
	v_cmp_gt_i32_e64 s[4:5], 4, v190
	s_or_b64 vcc, vcc, s[4:5]
	v_cndmask_b32_e32 v192, v192, v219, vcc
	v_cmp_lt_i32_e32 vcc, 5, v196
	v_cmp_gt_i32_e64 s[4:5], 5, v190
	s_or_b64 vcc, vcc, s[4:5]
	v_cndmask_b32_e32 v207, v193, v219, vcc
	v_cmp_lt_i32_e32 vcc, 6, v196
	v_cmp_gt_i32_e64 s[4:5], 6, v190
	s_or_b64 vcc, vcc, s[4:5]
	v_max3_f32 v197, v200, s41, v202
	v_cndmask_b32_e32 v208, v194, v219, vcc
	v_cmp_lt_i32_e32 vcc, 7, v196
	v_cmp_gt_i32_e64 s[4:5], 7, v190
	v_max3_f32 v197, v197, v205, v206
	s_or_b64 vcc, vcc, s[4:5]
	v_max3_f32 v193, v197, v192, v207
	v_cndmask_b32_e32 v210, v195, v219, vcc
	v_max3_f32 v190, v193, v208, v210
	v_mov_b32_e32 v194, v190
	s_nop 1
	v_permlane16_swap_b32_e32 v190, v194
	v_sub_f32_e32 v184, v184, v143
	v_exp_f32_e32 v193, v184
	v_sub_f32_e32 v184, v198, v143
	v_exp_f32_e32 v195, v184
	v_sub_f32_e32 v184, v186, v143
	s_waitcnt lgkmcnt(0)
; __device__ __forceinline__ void attn_step(int ks, const KVB& b, int L16, int r, int i0, int iq, int lane,
;                                           const bf16x8* qs, f32x4 (&o)[4], float& mrun, float& lrun) {
;   asm volatile("" : "+v"(lane), "+v"(iq));
;   asm volatile("" : "+s"(r), "+s"(i0));
;   const int quad = lane >> 4;
;   bf16x8 qB0 = qs[0], qB1 = qs[64];
;   int cV, sV; attn_desc(ks, quad, r, i0, cV, sV);
;   int D = ks < 12 ? 4 : (ks < 18 ? 16 : 64);
;   f32x4 z = {0.f, 0.f, 0.f, 0.f};
;   f32x4 sa = __builtin_amdgcn_mfma_f32_16x16x32_bf16(b.k0, qB0, z, 0, 0, 0);
;   sa = __builtin_amdgcn_mfma_f32_16x16x32_bf16(b.k1, qB1, sa, 0, 0, 0);
;   f32x4 sb = __builtin_amdgcn_mfma_f32_16x16x32_bf16(b.k2, qB0, z, 0, 0, 0);
;   sb = __builtin_amdgcn_mfma_f32_16x16x32_bf16(b.k3, qB1, sb, 0, 0, 0);
;   int jlo = max(iq - D + (cV < r ? 1 : 0), 0) - sV;
;   int jhi = min(iq + D - (cV > r ? 1 : 0), L16 - 1) - sV;
;   const float NINF = -__builtin_inff();
;   float s8[8];
;   float mt = -1e30f;
; #pragma unroll
;   for (int j = 0; j < 8; ++j) {
;     float sv = j < 4 ? sa[j] : sb[j - 4];
;     sv = (j >= jlo && j <= jhi) ? sv : NINF;
;     s8[j] = sv;
;     mt = fmaxf(mt, sv);
;   }
;   mt = fmaxf(mt, __shfl_xor(mt, 16));
;   mt = fmaxf(mt, __shfl_xor(mt, 32));
;   float mnew = fmaxf(mrun, mt);
;   float alpha = __builtin_amdgcn_exp2f(mrun - mnew);
;   mrun = mnew;
;   float ps = 0.f;
;   float p8[8];
; #pragma unroll
;   for (int j = 0; j < 8; ++j) { p8[j] = __builtin_amdgcn_exp2f(s8[j] - mnew); ps += p8[j]; }
;   lrun = lrun * alpha + ps;
;   union { uint4 u; bf16x8 v; } pb;
;   pb.u = make_uint4(pack2(p8[0], p8[1]), pack2(p8[2], p8[3]), pack2(p8[4], p8[5]), pack2(p8[6], p8[7]));
; #pragma unroll
;   for (int dt = 0; dt < 4; ++dt) { o[dt][0] *= alpha; o[dt][1] *= alpha; o[dt][2] *= alpha; o[dt][3] *= alpha; }
;   o[0] = __builtin_amdgcn_mfma_f32_16x16x32_bf16(b.v0, pb.v, o[0], 0, 0, 0);
;   o[1] = __builtin_amdgcn_mfma_f32_16x16x32_bf16(b.v1, pb.v, o[1], 0, 0, 0);
;   o[2] = __builtin_amdgcn_mfma_f32_16x16x32_bf16(b.v2, pb.v, o[2], 0, 0, 0);
;   o[3] = __builtin_amdgcn_mfma_f32_16x16x32_bf16(b.v3, pb.v, o[3], 0, 0, 0);
	v_max_f32_e32 v186, v194, v194
	v_max_f32_e32 v186, v190, v186
	v_mov_b32_e32 v190, v186
	s_nop 1
	v_permlane32_swap_b32_e32 v186, v190
	v_sub_f32_e32 v183, v183, v143
	v_exp_f32_e32 v197, v184
	v_sub_f32_e32 v184, v188, v143
	v_exp_f32_e32 v198, v183
	s_waitcnt lgkmcnt(0)
	v_max3_f32 v237, v165, v186, v190
	v_sub_f32_e32 v183, v200, v237
	v_exp_f32_e32 v201, v184
	v_exp_f32_e32 v184, v183
	v_sub_f32_e32 v183, v202, v237
	v_exp_f32_e32 v186, v183
	v_sub_f32_e32 v183, v205, v237
	v_exp_f32_e32 v188, v183
	v_sub_f32_e32 v183, v206, v237
	v_exp_f32_e32 v190, v183
	v_sub_f32_e32 v183, v192, v237
	v_exp_f32_e32 v192, v183
	v_sub_f32_e32 v183, v207, v237
	v_exp_f32_e32 v194, v183
	v_sub_f32_e32 v183, v208, v237
	v_sub_f32_e32 v165, v165, v237
	v_exp_f32_e32 v196, v183
	v_sub_f32_e32 v183, v210, v237
	v_exp_f32_e32 v200, v183
	v_exp_f32_e32 v202, v165
	s_mov_b32 s4, s8
	s_mov_b32 s5, s46
	ds_read_b128 v[210:213], v228 offset:4096
	ds_read_b128 v[214:217], v228 offset:5120
	v_add_u32_e32 v205, s22, v246
	v_and_or_b32 v165, s4, 3, v247
	s_waitcnt lgkmcnt(1)
	v_mfma_f32_16x16x32_bf16 v[220:223], v[108:111], v[210:213], 0
	v_cndmask_b32_e64 v165, v165, v205, s[0:1]
	v_cmp_gt_i32_e32 vcc, s4, v165
	s_add_i32 s24, s5, s23
	v_cmp_lt_i32_e64 s[4:5], s4, v165
	v_addc_co_u32_e32 v205, vcc, v225, v218, vcc
	v_add_u32_e32 v183, s61, v225
	v_subbrev_co_u32_e64 v165, s[4:5], 0, v183, s[4:5]
	s_waitcnt lgkmcnt(0)
	v_mfma_f32_16x16x32_bf16 v[220:223], v[104:107], v[214:217], v[220:223]
	v_max_i32_e32 v205, 0, v205
	v_min_i32_e32 v165, s43, v165
	v_subrev_u32_e32 v205, s24, v205
	v_subrev_u32_e32 v165, s24, v165
	v_mfma_f32_16x16x32_bf16 v[210:213], v[100:103], v[210:213], 0
	v_cmp_lt_i32_e32 vcc, 0, v205
	v_cmp_gt_i32_e64 s[4:5], 0, v165
	s_or_b64 vcc, vcc, s[4:5]
	v_cndmask_b32_e32 v183, v220, v219, vcc
	v_cmp_lt_i32_e32 vcc, 1, v205
	v_cmp_gt_i32_e64 s[4:5], 1, v165
	s_or_b64 vcc, vcc, s[4:5]
	v_mfma_f32_16x16x32_bf16 v[210:213], v[96:99], v[214:217], v[210:213]
	v_cndmask_b32_e32 v214, v221, v219, vcc
	v_cmp_lt_i32_e32 vcc, 2, v205
	v_cmp_gt_i32_e64 s[4:5], 2, v165
	s_or_b64 vcc, vcc, s[4:5]
	v_cndmask_b32_e32 v216, v222, v219, vcc
	v_cmp_lt_i32_e32 vcc, 3, v205
	v_cmp_gt_i32_e64 s[4:5], 3, v165
	s_or_b64 vcc, vcc, s[4:5]
	v_cndmask_b32_e32 v217, v223, v219, vcc
	v_cmp_lt_i32_e32 vcc, 4, v205
	v_cmp_gt_i32_e64 s[4:5], 4, v165
	s_or_b64 vcc, vcc, s[4:5]
	v_cndmask_b32_e32 v210, v210, v219, vcc
	v_cmp_lt_i32_e32 vcc, 5, v205
	v_cmp_gt_i32_e64 s[4:5], 5, v165
	s_or_b64 vcc, vcc, s[4:5]
	v_cndmask_b32_e32 v235, v211, v219, vcc
	v_cmp_lt_i32_e32 vcc, 6, v205
	v_cmp_gt_i32_e64 s[4:5], 6, v165
	s_or_b64 vcc, vcc, s[4:5]
	v_max3_f32 v215, v183, s41, v214
	v_cndmask_b32_e32 v242, v212, v219, vcc
	v_cmp_lt_i32_e32 vcc, 7, v205
	v_cmp_gt_i32_e64 s[4:5], 7, v165
	v_max3_f32 v215, v215, v216, v217
	s_or_b64 vcc, vcc, s[4:5]
	v_max3_f32 v211, v215, v210, v235
	v_cndmask_b32_e32 v165, v213, v219, vcc
	v_max3_f32 v205, v211, v242, v165
	v_mov_b32_e32 v211, v205
	s_nop 1
	v_permlane16_swap_b32_e32 v205, v211
	v_exp_f32_e32 v185, v185
	v_exp_f32_e32 v187, v187
	v_exp_f32_e32 v189, v189
	v_exp_f32_e32 v191, v191
	s_waitcnt lgkmcnt(0)
	v_max_f32_e32 v205, v205, v211
	v_mov_b32_e32 v211, v205
	s_nop 1
	v_permlane32_swap_b32_e32 v205, v211
	v_pk_mul_f32 v[62:63], v[62:63], v[198:199] op_sel_hi:[1,0]
	v_pk_mul_f32 v[60:61], v[60:61], v[198:199] op_sel_hi:[1,0]
	v_cvt_pk_bf16_f32 v206, v185, v187
	v_cvt_pk_bf16_f32 v207, v189, v191
	v_cvt_pk_bf16_f32 v208, v193, v195
	v_cvt_pk_bf16_f32 v209, v197, v201
	v_pk_mul_f32 v[58:59], v[58:59], v[198:199] op_sel_hi:[1,0]
	v_pk_mul_f32 v[56:57], v[56:57], v[198:199] op_sel_hi:[1,0]
	v_pk_mul_f32 v[54:55], v[54:55], v[198:199] op_sel_hi:[1,0]
	v_pk_mul_f32 v[52:53], v[52:53], v[198:199] op_sel_hi:[1,0]
	v_pk_mul_f32 v[46:47], v[46:47], v[198:199] op_sel_hi:[1,0]
	v_pk_mul_f32 v[44:45], v[44:45], v[198:199] op_sel_hi:[1,0]
	s_waitcnt vmcnt(15)
	v_mfma_f32_16x16x32_bf16 v[60:63], v[80:83], v[206:209], v[60:63]
	v_mul_f32_e64 v50, v50, v202
	v_mul_f32_e64 v51, v51, v202
	v_pk_mul_f32 v[48:49], v[48:49], v[202:203] op_sel_hi:[1,0]
	v_pk_mul_f32 v[42:43], v[42:43], v[202:203] op_sel_hi:[1,0]
	s_waitcnt vmcnt(14)
	v_mfma_f32_16x16x32_bf16 v[56:59], v[84:87], v[206:209], v[56:59]
	v_mul_f32_e64 v40, v40, v202
	v_mul_f32_e64 v41, v41, v202
	v_pk_mul_f32 v[38:39], v[38:39], v[202:203] op_sel_hi:[1,0]
	v_pk_mul_f32 v[36:37], v[36:37], v[202:203] op_sel_hi:[1,0]
	s_waitcnt vmcnt(13)
	v_mfma_f32_16x16x32_bf16 v[52:55], v[88:91], v[206:209], v[52:55]
	v_mul_f32_e64 v30, v30, v202
	v_mul_f32_e64 v31, v31, v202
	v_pk_mul_f32 v[28:29], v[28:29], v[202:203] op_sel_hi:[1,0]
	s_waitcnt lgkmcnt(0)
	v_max3_f32 v236, v204, v205, v211
	s_waitcnt vmcnt(12)
	v_mfma_f32_16x16x32_bf16 v[44:47], v[92:95], v[206:209], v[44:47]
	v_cvt_pk_bf16_f32 v206, v184, v186
	v_cvt_pk_bf16_f32 v207, v188, v190
	v_cvt_pk_bf16_f32 v208, v192, v194
	v_cvt_pk_bf16_f32 v209, v196, v200
	v_sub_f32_e32 v183, v183, v236
	s_mov_b32 s4, s10
	v_mfma_f32_16x16x32_bf16 v[48:51], v[80:83], v[206:209], v[48:51]
	s_mov_b32 s5, s46
	v_exp_f32_e32 v205, v183
	v_sub_f32_e32 v183, v214, v236
	v_mfma_f32_16x16x32_bf16 v[40:43], v[84:87], v[206:209], v[40:43]
	v_sub_f32_e32 v204, v204, v236
	s_mov_b64 s[24:25], -1
	v_mfma_f32_16x16x32_bf16 v[36:39], v[88:91], v[206:209], v[36:39]
	v_mfma_f32_16x16x32_bf16 v[28:31], v[92:95], v[206:209], v[28:31]
	ds_read_b128 v[212:215], v228 offset:6144
	ds_read_b128 v[220:223], v228 offset:7168
	s_waitcnt lgkmcnt(1)
; __device__ __forceinline__ void attn_step(int ks, const KVB& b, int L16, int r, int i0, int iq, int lane,
;                                           const bf16x8* qs, f32x4 (&o)[4], float& mrun, float& lrun) {
;   asm volatile("" : "+v"(lane), "+v"(iq));
;   asm volatile("" : "+s"(r), "+s"(i0));
;   const int quad = lane >> 4;
;   bf16x8 qB0 = qs[0], qB1 = qs[64];
;   int cV, sV; attn_desc(ks, quad, r, i0, cV, sV);
;   int D = ks < 12 ? 4 : (ks < 18 ? 16 : 64);
;   f32x4 z = {0.f, 0.f, 0.f, 0.f};
;   f32x4 sa = __builtin_amdgcn_mfma_f32_16x16x32_bf16(b.k0, qB0, z, 0, 0, 0);
;   sa = __builtin_amdgcn_mfma_f32_16x16x32_bf16(b.k1, qB1, sa, 0, 0, 0);
;   f32x4 sb = __builtin_amdgcn_mfma_f32_16x16x32_bf16(b.k2, qB0, z, 0, 0, 0);
;   sb = __builtin_amdgcn_mfma_f32_16x16x32_bf16(b.k3, qB1, sb, 0, 0, 0);
;   int jlo = max(iq - D + (cV < r ? 1 : 0), 0) - sV;
;   int jhi = min(iq + D - (cV > r ? 1 : 0), L16 - 1) - sV;
;   const float NINF = -__builtin_inff();
;   float s8[8];
;   float mt = -1e30f;
; #pragma unroll
;   for (int j = 0; j < 8; ++j) {
;     float sv = j < 4 ? sa[j] : sb[j - 4];
;     sv = (j >= jlo && j <= jhi) ? sv : NINF;
;     s8[j] = sv;
;     mt = fmaxf(mt, sv);
;   }
;   mt = fmaxf(mt, __shfl_xor(mt, 16));
;   mt = fmaxf(mt, __shfl_xor(mt, 32));
;   float mnew = fmaxf(mrun, mt);
;   float alpha = __builtin_amdgcn_exp2f(mrun - mnew);
;   mrun = mnew;
;   float ps = 0.f;
;   float p8[8];
; #pragma unroll
;   for (int j = 0; j < 8; ++j) { p8[j] = __builtin_amdgcn_exp2f(s8[j] - mnew); ps += p8[j]; }
;   lrun = lrun * alpha + ps;
;   union { uint4 u; bf16x8 v; } pb;
;   pb.u = make_uint4(pack2(p8[0], p8[1]), pack2(p8[2], p8[3]), pack2(p8[4], p8[5]), pack2(p8[6], p8[7]));
; #pragma unroll
;   for (int dt = 0; dt < 4; ++dt) { o[dt][0] *= alpha; o[dt][1] *= alpha; o[dt][2] *= alpha; o[dt][3] *= alpha; }
;   o[0] = __builtin_amdgcn_mfma_f32_16x16x32_bf16(b.v0, pb.v, o[0], 0, 0, 0);
;   o[1] = __builtin_amdgcn_mfma_f32_16x16x32_bf16(b.v1, pb.v, o[1], 0, 0, 0);
;   o[2] = __builtin_amdgcn_mfma_f32_16x16x32_bf16(b.v2, pb.v, o[2], 0, 0, 0);
;   o[3] = __builtin_amdgcn_mfma_f32_16x16x32_bf16(b.v3, pb.v, o[3], 0, 0, 0);
; template <int NT>
; __device__ void attn_unitN(const P& p, int u) {
;     ...
;     bB = attn_load_e<NT>(ks + 3, kbase, vbase, L16, rb, i0, lane);
	v_mfma_f32_16x16x32_bf16 v[108:111], v[108:111], v[212:215], 0
	s_add_i32 s5, s5, s23
	v_exp_f32_e32 v207, v183
	v_sub_f32_e32 v183, v216, v236
	s_waitcnt lgkmcnt(0)
	v_mfma_f32_16x16x32_bf16 v[104:107], v[104:107], v[220:223], v[108:111]
	v_exp_f32_e32 v209, v183
	v_sub_f32_e32 v183, v217, v236
	v_exp_f32_e32 v211, v183
	v_mfma_f32_16x16x32_bf16 v[100:103], v[100:103], v[212:215], 0
	v_add_u32_e32 v109, s22, v246
	v_and_or_b32 v108, s4, 3, v247
	v_cndmask_b32_e64 v108, v108, v109, s[0:1]
	v_mfma_f32_16x16x32_bf16 v[96:99], v[96:99], v[220:223], v[100:103]
	v_cmp_gt_i32_e32 vcc, s4, v108
	v_cmp_lt_i32_e64 s[0:1], s4, v108
	v_sub_f32_e32 v183, v210, v236
	s_nop 0
	v_add_u32_e32 v101, s61, v225
	v_addc_co_u32_e32 v100, vcc, v225, v218, vcc
	v_subbrev_co_u32_e64 v101, s[0:1], 0, v101, s[0:1]
	v_max_i32_e32 v100, 0, v100
	v_min_i32_e32 v101, s43, v101
	v_subrev_u32_e32 v100, s5, v100
	v_subrev_u32_e32 v101, s5, v101
	v_cmp_lt_i32_e32 vcc, 0, v100
	v_cmp_gt_i32_e64 s[0:1], 0, v101
	s_or_b64 vcc, vcc, s[0:1]
	v_cndmask_b32_e32 v102, v104, v219, vcc
	v_cmp_lt_i32_e32 vcc, 1, v100
	v_cmp_gt_i32_e64 s[0:1], 1, v101
	s_or_b64 vcc, vcc, s[0:1]
	v_cndmask_b32_e32 v103, v105, v219, vcc
	v_cmp_lt_i32_e32 vcc, 2, v100
	v_cmp_gt_i32_e64 s[0:1], 2, v101
	s_or_b64 vcc, vcc, s[0:1]
	v_cndmask_b32_e32 v105, v106, v219, vcc
	v_cmp_lt_i32_e32 vcc, 3, v100
	v_cmp_gt_i32_e64 s[0:1], 3, v101
	s_or_b64 vcc, vcc, s[0:1]
	v_cndmask_b32_e32 v106, v107, v219, vcc
	v_cmp_lt_i32_e32 vcc, 4, v100
	v_cmp_gt_i32_e64 s[0:1], 4, v101
	s_or_b64 vcc, vcc, s[0:1]
	v_cndmask_b32_e32 v96, v96, v219, vcc
	v_cmp_lt_i32_e32 vcc, 5, v100
	v_cmp_gt_i32_e64 s[0:1], 5, v101
	s_or_b64 vcc, vcc, s[0:1]
	v_cndmask_b32_e32 v97, v97, v219, vcc
	v_cmp_lt_i32_e32 vcc, 6, v100
	v_cmp_gt_i32_e64 s[0:1], 6, v101
	s_or_b64 vcc, vcc, s[0:1]
	v_max3_f32 v104, v102, s41, v103
	v_cndmask_b32_e32 v98, v98, v219, vcc
	v_cmp_lt_i32_e32 vcc, 7, v100
	v_cmp_gt_i32_e64 s[0:1], 7, v101
	v_max3_f32 v104, v104, v105, v106
	s_or_b64 vcc, vcc, s[0:1]
	v_max3_f32 v104, v104, v96, v97
	v_cndmask_b32_e32 v100, v99, v219, vcc
	v_max3_f32 v99, v104, v98, v100
	v_mov_b32_e32 v101, v99
	s_nop 1
	v_permlane16_swap_b32_e32 v99, v101
	v_sub_f32_e32 v104, v235, v236
	v_exp_f32_e32 v215, v104
	v_sub_f32_e32 v104, v242, v236
	v_exp_f32_e32 v218, v204
	s_waitcnt lgkmcnt(0)
	v_max_f32_e32 v99, v99, v101
	v_mov_b32_e32 v101, v99
	s_nop 1
	v_permlane32_swap_b32_e32 v99, v101
	v_exp_f32_e32 v217, v104
	v_sub_f32_e32 v104, v165, v236
	v_exp_f32_e32 v213, v183
	v_exp_f32_e32 v221, v104
	s_waitcnt lgkmcnt(0)
	v_max3_f32 v235, v203, v99, v101
	v_sub_f32_e32 v99, v102, v235
	v_exp_f32_e32 v204, v99
	v_sub_f32_e32 v99, v103, v235
	v_sub_f32_e32 v96, v96, v235
	v_exp_f32_e32 v206, v99
	v_sub_f32_e32 v99, v105, v235
	v_exp_f32_e32 v212, v96
	v_sub_f32_e32 v96, v97, v235
	v_sub_f32_e32 v101, v203, v235
	v_exp_f32_e32 v208, v99
	v_sub_f32_e32 v99, v106, v235
	v_exp_f32_e32 v214, v96
	v_sub_f32_e32 v96, v98, v235
	v_sub_f32_e32 v100, v100, v235
	s_and_b32 s0, s59, 12
	v_exp_f32_e32 v210, v99
	v_exp_f32_e32 v216, v96
	v_exp_f32_e32 v220, v100
	v_exp_f32_e32 v222, v101
	s_add_i32 s22, s60, 3
	s_xor_b32 s23, s0, 8
	s_cmp_gt_u32 s60, 14
	s_cselect_b64 s[4:5], -1, 0
	v_pk_mul_f32 v[34:35], v[34:35], v[218:219] op_sel_hi:[1,0]
	v_pk_mul_f32 v[32:33], v[32:33], v[218:219] op_sel_hi:[1,0]
	v_cvt_pk_bf16_f32 v96, v205, v207
	v_cvt_pk_bf16_f32 v97, v209, v211
	v_cvt_pk_bf16_f32 v98, v213, v215
	v_cvt_pk_bf16_f32 v99, v217, v221
	v_pk_mul_f32 v[26:27], v[26:27], v[218:219] op_sel_hi:[1,0]
	v_pk_mul_f32 v[24:25], v[24:25], v[218:219] op_sel_hi:[1,0]
	v_pk_mul_f32 v[22:23], v[22:23], v[218:219] op_sel_hi:[1,0]
	v_pk_mul_f32 v[20:21], v[20:21], v[218:219] op_sel_hi:[1,0]
	v_pk_mul_f32 v[14:15], v[14:15], v[218:219] op_sel_hi:[1,0]
	v_pk_mul_f32 v[12:13], v[12:13], v[218:219] op_sel_hi:[1,0]
	s_and_b64 s[0:1], s[4:5], exec
	v_mfma_f32_16x16x32_bf16 v[32:35], v[80:83], v[96:99], v[32:35]
	v_mul_f32_e64 v18, v18, v222
	v_mul_f32_e64 v19, v19, v222
	v_pk_mul_f32 v[16:17], v[16:17], v[222:223] op_sel_hi:[1,0]
	v_pk_mul_f32 v[10:11], v[10:11], v[222:223] op_sel_hi:[1,0]
	v_mfma_f32_16x16x32_bf16 v[24:27], v[84:87], v[96:99], v[24:27]
	v_mul_f32_e64 v8, v8, v222
	v_mul_f32_e64 v9, v9, v222
	v_pk_mul_f32 v[6:7], v[6:7], v[222:223] op_sel_hi:[1,0]
	v_pk_mul_f32 v[4:5], v[4:5], v[222:223] op_sel_hi:[1,0]
	v_mfma_f32_16x16x32_bf16 v[20:23], v[88:91], v[96:99], v[20:23]
	v_mul_f32_e64 v2, v2, v222
	v_mul_f32_e64 v3, v3, v222
	v_pk_mul_f32 v[0:1], v[0:1], v[222:223] op_sel_hi:[1,0]
	s_cselect_b32 s63, s23, 0
	v_mfma_f32_16x16x32_bf16 v[12:15], v[92:95], v[96:99], v[12:15]
	v_cvt_pk_bf16_f32 v96, v204, v206
	v_cvt_pk_bf16_f32 v97, v208, v210
	v_cvt_pk_bf16_f32 v98, v212, v214
	v_cvt_pk_bf16_f32 v99, v216, v220
	s_add_i32 s63, s63, s42
	s_min_u32 s61, s22, 18
	v_mfma_f32_16x16x32_bf16 v[16:19], v[80:83], v[96:99], v[16:19]
	s_cmp_gt_u32 s60, 8
	s_cselect_b64 s[22:23], -1, 0
	s_and_b64 vcc, exec, s[22:23]
	v_mfma_f32_16x16x32_bf16 v[8:11], v[84:87], v[96:99], v[8:11]
	v_mfma_f32_16x16x32_bf16 v[4:7], v[88:91], v[96:99], v[4:7]
	v_mfma_f32_16x16x32_bf16 v[0:3], v[92:95], v[96:99], v[0:3]
	s_cbranch_vccz .LBB0_254
	s_mov_b64 vcc, s[0:1]
	s_cbranch_vccz .LBB0_251
	v_lshl_add_u32 v80, s61, 5, v231
	s_mov_b64 s[24:25], 0

; __device__ __forceinline__ void attn_step(int ks, const KVB& b, int L16, int r, int i0, int iq, int lane,
;                                           const bf16x8* qs, f32x4 (&o)[4], float& mrun, float& lrun) {
;   asm volatile("" : "+v"(lane), "+v"(iq));
;   asm volatile("" : "+s"(r), "+s"(i0));
;   const int quad = lane >> 4;
;   bf16x8 qB0 = qs[0], qB1 = qs[64];
;   int cV, sV; attn_desc(ks, quad, r, i0, cV, sV);
;   int D = ks < 12 ? 4 : (ks < 18 ? 16 : 64);
;   f32x4 z = {0.f, 0.f, 0.f, 0.f};
;   f32x4 sa = __builtin_amdgcn_mfma_f32_16x16x32_bf16(b.k0, qB0, z, 0, 0, 0);
;   sa = __builtin_amdgcn_mfma_f32_16x16x32_bf16(b.k1, qB1, sa, 0, 0, 0);
;   f32x4 sb = __builtin_amdgcn_mfma_f32_16x16x32_bf16(b.k2, qB0, z, 0, 0, 0);
;   sb = __builtin_amdgcn_mfma_f32_16x16x32_bf16(b.k3, qB1, sb, 0, 0, 0);
;   int jlo = max(iq - D + (cV < r ? 1 : 0), 0) - sV;
;   int jhi = min(iq + D - (cV > r ? 1 : 0), L16 - 1) - sV;
;   const float NINF = -__builtin_inff();
;   float s8[8];
;   float mt = -1e30f;
; #pragma unroll
;   for (int j = 0; j < 8; ++j) {
;     float sv = j < 4 ? sa[j] : sb[j - 4];
;     sv = (j >= jlo && j <= jhi) ? sv : NINF;
;     s8[j] = sv;
;     mt = fmaxf(mt, sv);
;   }
;   mt = fmaxf(mt, __shfl_xor(mt, 16));
;   mt = fmaxf(mt, __shfl_xor(mt, 32));
;   float mnew = fmaxf(mrun, mt);
;   float alpha = __builtin_amdgcn_exp2f(mrun - mnew);
;   mrun = mnew;
;   float ps = 0.f;
;   float p8[8];
; #pragma unroll
;   for (int j = 0; j < 8; ++j) { p8[j] = __builtin_amdgcn_exp2f(s8[j] - mnew); ps += p8[j]; }
; template <int NT>
; __device__ void attn_unitN(const P& p, int u) {
;     ...
;   for (int kk = 0; kk < 5; ++kk) {
;     int e0 = 18 + NT * kk, ks = 18 + kk;
; #pragma unroll
;     for (int t = 0; t < NT; t += 2) {
;       attn_step(ks, bA, L16, rb + RS * t, i0, iq, lane, qs + t * 128, o[t], mrun[t], lrun[t]);
;       { int f = min(e0 + t + 2, EMAX) - 18;
;         bA = attn_load(18 + f / NT, kbase, vbase, L16, rb + RS * (f % NT), i0, lane); }
;       attn_step(ks, bB, L16, rb + RS * (t + 1), i0, iq, lane, qs + (t + 1) * 128, o[t + 1], mrun[t + 1], lrun[t + 1]);
;       { int f = min(e0 + t + 3, EMAX) - 18;
;         bB = attn_load(18 + f / NT, kbase, vbase, L16, rb + RS * (f % NT), i0, lane); }
;     }
.LBB0_267:
	s_mov_b32 s0, s42
	s_mov_b32 s1, s46
	ds_read_b128 v[128:131], v228
	ds_read_b128 v[132:135], v228 offset:1024
	s_waitcnt vmcnt(21) lgkmcnt(1)
	v_mfma_f32_16x16x32_bf16 v[116:119], v[116:119], v[128:131], 0
	s_sub_i32 s0, s1, 64
	v_add_u32_e32 v136, s11, v246
	v_mfma_f32_16x16x32_bf16 v[124:127], v[124:127], v[128:131], 0
	v_lshl_add_u32 v136, v136, 3, s0
	v_ashrrev_i32_e32 v192, 2, v180
	v_ashrrev_i32_e32 v193, 31, v192
	s_waitcnt vmcnt(20) lgkmcnt(0)
	v_mfma_f32_16x16x32_bf16 v[112:115], v[112:115], v[132:135], v[116:119]
	v_lshl_add_u64 v[128:129], s[4:5], 0, v[192:193]
	v_lshlrev_b64 v[128:129], 9, v[128:129]
	s_nop 0
	v_subrev_u32_e32 v116, 64, v225
	v_add_u32_e32 v117, 64, v225
	v_mfma_f32_16x16x32_bf16 v[120:123], v[120:123], v[132:135], v[124:127]
	v_max_i32_e32 v116, 0, v116
	v_min_i32_e32 v117, s43, v117
	v_sub_u32_e32 v116, v116, v136
	v_sub_u32_e32 v117, v117, v136
	v_cmp_lt_i32_e32 vcc, 0, v116
	v_cmp_gt_i32_e64 s[0:1], 0, v117
	s_or_b64 vcc, vcc, s[0:1]
	s_nop 0
	v_cndmask_b32_e32 v118, v120, v219, vcc
	v_cmp_lt_i32_e32 vcc, 1, v116
	v_cmp_gt_i32_e64 s[0:1], 1, v117
	s_or_b64 vcc, vcc, s[0:1]
	v_cndmask_b32_e32 v119, v121, v219, vcc
	v_cmp_lt_i32_e32 vcc, 2, v116
	v_cmp_gt_i32_e64 s[0:1], 2, v117
	s_or_b64 vcc, vcc, s[0:1]
	v_cndmask_b32_e32 v121, v122, v219, vcc
	v_cmp_lt_i32_e32 vcc, 3, v116
	v_cmp_gt_i32_e64 s[0:1], 3, v117
	s_or_b64 vcc, vcc, s[0:1]
	v_cndmask_b32_e32 v122, v123, v219, vcc
	v_cmp_lt_i32_e32 vcc, 4, v116
	v_cmp_gt_i32_e64 s[0:1], 4, v117
	s_or_b64 vcc, vcc, s[0:1]
	v_cndmask_b32_e32 v112, v112, v219, vcc
	v_cmp_lt_i32_e32 vcc, 5, v116
	v_cmp_gt_i32_e64 s[0:1], 5, v117
	s_or_b64 vcc, vcc, s[0:1]
	v_cndmask_b32_e32 v113, v113, v219, vcc
	v_cmp_lt_i32_e32 vcc, 6, v116
	v_cmp_gt_i32_e64 s[0:1], 6, v117
	s_or_b64 vcc, vcc, s[0:1]
	v_max3_f32 v120, v118, s41, v119
	v_cndmask_b32_e32 v114, v114, v219, vcc
	v_cmp_lt_i32_e32 vcc, 7, v116
	v_cmp_gt_i32_e64 s[0:1], 7, v117
	v_max3_f32 v120, v120, v121, v122
	s_or_b64 vcc, vcc, s[0:1]
	v_max3_f32 v120, v120, v112, v113
	v_cndmask_b32_e32 v115, v115, v219, vcc
	v_max3_f32 v116, v120, v114, v115
	v_mov_b32_e32 v117, v116
	s_nop 1
	v_permlane16_swap_b32_e32 v116, v117
	s_mov_b32 s0, s56
	s_mov_b32 s1, s46
	s_add_i32 s22, s11, 20
	v_add_u32_e32 v180, 32, v180
	s_waitcnt lgkmcnt(0)
	v_max_f32_e32 v116, v116, v117
	v_mov_b32_e32 v117, v116
	s_nop 1
	v_permlane32_swap_b32_e32 v116, v117
	s_waitcnt lgkmcnt(0)
	v_max3_f32 v182, v143, v116, v117
	v_sub_f32_e32 v112, v112, v182
	v_exp_f32_e32 v171, v112
	v_sub_f32_e32 v112, v113, v182
	v_exp_f32_e32 v173, v112
	v_sub_f32_e32 v112, v114, v182
	v_exp_f32_e32 v175, v112
	v_sub_f32_e32 v112, v115, v182
	v_exp_f32_e32 v177, v112
	v_max_i32_e32 v112, 0, v181
	v_max_i32_e32 v113, -4, v181
	v_sub_f32_e32 v117, v118, v182
	v_min_i32_e32 v112, s43, v112
	v_add_u32_e32 v113, 4, v113
	v_exp_f32_e32 v163, v117
	v_sub_f32_e32 v117, v119, v182
	v_min_u32_e32 v114, s43, v113
	v_lshlrev_b32_e32 v194, 4, v112
	v_exp_f32_e32 v165, v117
	v_sub_f32_e32 v117, v121, v182
	v_add_u32_e32 v144, s8, v194
	v_lshlrev_b32_e32 v195, 4, v114
	v_sub_f32_e32 v116, v143, v182
	v_exp_f32_e32 v167, v117
	v_sub_f32_e32 v117, v122, v182
	v_lshrrev_b32_e32 v243, 8, v144
	v_and_b32_e32 v244, 15, v144
	v_lshlrev_b32_e32 v243, 18, v243
	v_lshl_or_b32 v243, v244, 11, v243
	v_bfe_u32 v244, v144, 6, 2
	v_lshl_or_b32 v243, v244, 9, v243
	v_bfe_u32 v244, v144, 4, 2
	v_lshl_or_b32 v112, v244, 5, v243
	v_mov_b32_e32 v113, 0
	v_add_u32_e32 v144, s8, v195
	v_exp_f32_e32 v169, v117
	v_exp_f32_e32 v179, v116
	v_lshl_add_u64 v[116:117], v[154:155], 0, v[112:113]
	v_lshrrev_b32_e32 v243, 8, v144
	v_and_b32_e32 v244, 15, v144
	v_lshlrev_b32_e32 v243, 18, v243
	v_lshl_or_b32 v243, v244, 11, v243
	v_bfe_u32 v244, v144, 6, 2
	v_lshl_or_b32 v243, v244, 9, v243
	v_bfe_u32 v244, v144, 4, 2
	v_lshl_or_b32 v112, v244, 5, v243
	v_mov_b32_e32 v113, 0
	v_lshl_add_u64 v[124:125], v[154:155], 0, v[112:113]
	global_load_dwordx4 v[112:115], v[116:117], off
	s_nop 0
	global_load_dwordx4 v[116:119], v[116:117], off offset:16
	s_nop 0
	global_load_dwordx4 v[120:123], v[124:125], off
	s_nop 0
	global_load_dwordx4 v[124:127], v[124:125], off offset:16
	v_lshl_add_u64 v[142:143], v[158:159], 0, v[128:129]
	global_load_dwordx2 v[128:129], v[142:143], off
	global_load_dwordx2 v[130:131], v[142:143], off offset:512
	global_load_dwordx2 v[132:133], v[142:143], off offset:128
	global_load_dwordx2 v[134:135], v[142:143], off offset:640
	global_load_dwordx2 v[136:137], v[142:143], off offset:256
	global_load_dwordx2 v[138:139], v[142:143], off offset:768
	global_load_dwordx2 v[140:141], v[142:143], off offset:384
	s_nop 0
	global_load_dwordx2 v[142:143], v[142:143], off offset:896
	ds_read_b128 v[184:187], v228 offset:2048
	ds_read_b128 v[188:191], v228 offset:3072
	s_waitcnt vmcnt(21) lgkmcnt(1)
	v_mfma_f32_16x16x32_bf16 v[100:103], v[100:103], v[184:187], 0
	s_sub_i32 s0, s1, 64
	v_add_u32_e32 v144, s11, v246
	v_mfma_f32_16x16x32_bf16 v[108:111], v[108:111], v[184:187], 0
	v_lshl_add_u32 v144, v144, 3, s0
	v_add_u32_e32 v181, 32, v181
	s_waitcnt vmcnt(20) lgkmcnt(0)
; __device__ __forceinline__ void attn_step(int ks, const KVB& b, int L16, int r, int i0, int iq, int lane,
;                                           const bf16x8* qs, f32x4 (&o)[4], float& mrun, float& lrun) {
;     ...
;   f32x4 sa = __builtin_amdgcn_mfma_f32_16x16x32_bf16(b.k0, qB0, z, 0, 0, 0);
;   sa = __builtin_amdgcn_mfma_f32_16x16x32_bf16(b.k1, qB1, sa, 0, 0, 0);
;   f32x4 sb = __builtin_amdgcn_mfma_f32_16x16x32_bf16(b.k2, qB0, z, 0, 0, 0);
;   sb = __builtin_amdgcn_mfma_f32_16x16x32_bf16(b.k3, qB1, sb, 0, 0, 0);
;   int jlo = max(iq - D + (cV < r ? 1 : 0), 0) - sV;
;   int jhi = min(iq + D - (cV > r ? 1 : 0), L16 - 1) - sV;
;   const float NINF = -__builtin_inff();
;   float s8[8];
;   float mt = -1e30f;
; #pragma unroll
;   for (int j = 0; j < 8; ++j) {
;     float sv = j < 4 ? sa[j] : sb[j - 4];
;     sv = (j >= jlo && j <= jhi) ? sv : NINF;
;     s8[j] = sv;
;     mt = fmaxf(mt, sv);
;   }
;   mt = fmaxf(mt, __shfl_xor(mt, 16));
;   mt = fmaxf(mt, __shfl_xor(mt, 32));
;   float mnew = fmaxf(mrun, mt);
;   float alpha = __builtin_amdgcn_exp2f(mrun - mnew);
;   mrun = mnew;
;   float ps = 0.f;
;   float p8[8];
; #pragma unroll
;   for (int j = 0; j < 8; ++j) { p8[j] = __builtin_amdgcn_exp2f(s8[j] - mnew); ps += p8[j]; }
;   lrun = lrun * alpha + ps;
;   union { uint4 u; bf16x8 v; } pb;
;   pb.u = make_uint4(pack2(p8[0], p8[1]), pack2(p8[2], p8[3]), pack2(p8[4], p8[5]), pack2(p8[6], p8[7]));
; #pragma unroll
;   for (int dt = 0; dt < 4; ++dt) { o[dt][0] *= alpha; o[dt][1] *= alpha; o[dt][2] *= alpha; o[dt][3] *= alpha; }
;   o[0] = __builtin_amdgcn_mfma_f32_16x16x32_bf16(b.v0, pb.v, o[0], 0, 0, 0);
;   o[1] = __builtin_amdgcn_mfma_f32_16x16x32_bf16(b.v1, pb.v, o[1], 0, 0, 0);
;   o[2] = __builtin_amdgcn_mfma_f32_16x16x32_bf16(b.v2, pb.v, o[2], 0, 0, 0);
;   o[3] = __builtin_amdgcn_mfma_f32_16x16x32_bf16(b.v3, pb.v, o[3], 0, 0, 0);
; template <int NT>
; __device__ void attn_unitN(const P& p, int u) {
;     ...
;       { int f = min(e0 + t + 2, EMAX) - 18;
;         bA = attn_load(18 + f / NT, kbase, vbase, L16, rb + RS * (f % NT), i0, lane); }
;       attn_step(ks, bB, L16, rb + RS * (t + 1), i0, iq, lane, qs + (t + 1) * 128, o[t + 1], mrun[t + 1], lrun[t + 1]);
;       { int f = min(e0 + t + 3, EMAX) - 18;
;         bB = attn_load(18 + f / NT, kbase, vbase, L16, rb + RS * (f % NT), i0, lane); }
	v_mfma_f32_16x16x32_bf16 v[96:99], v[96:99], v[188:191], v[100:103]
	s_nop 2
	v_subrev_u32_e32 v100, 64, v225
	v_add_u32_e32 v101, 64, v225
	v_mfma_f32_16x16x32_bf16 v[104:107], v[104:107], v[188:191], v[108:111]
	v_max_i32_e32 v100, 0, v100
	v_min_i32_e32 v101, s43, v101
	v_sub_u32_e32 v100, v100, v144
	v_sub_u32_e32 v101, v101, v144
	v_cmp_lt_i32_e32 vcc, 0, v100
	v_cmp_gt_i32_e64 s[0:1], 0, v101
	s_or_b64 vcc, vcc, s[0:1]
	s_nop 0
	v_cndmask_b32_e32 v102, v104, v219, vcc
	v_cmp_lt_i32_e32 vcc, 1, v100
	v_cmp_gt_i32_e64 s[0:1], 1, v101
	s_or_b64 vcc, vcc, s[0:1]
	v_cndmask_b32_e32 v103, v105, v219, vcc
	v_cmp_lt_i32_e32 vcc, 2, v100
	v_cmp_gt_i32_e64 s[0:1], 2, v101
	s_or_b64 vcc, vcc, s[0:1]
	v_cndmask_b32_e32 v105, v106, v219, vcc
	v_cmp_lt_i32_e32 vcc, 3, v100
	v_cmp_gt_i32_e64 s[0:1], 3, v101
	s_or_b64 vcc, vcc, s[0:1]
	v_cndmask_b32_e32 v106, v107, v219, vcc
	v_cmp_lt_i32_e32 vcc, 4, v100
	v_cmp_gt_i32_e64 s[0:1], 4, v101
	s_or_b64 vcc, vcc, s[0:1]
	v_cndmask_b32_e32 v96, v96, v219, vcc
	v_cmp_lt_i32_e32 vcc, 5, v100
	v_cmp_gt_i32_e64 s[0:1], 5, v101
	s_or_b64 vcc, vcc, s[0:1]
	v_cndmask_b32_e32 v97, v97, v219, vcc
	v_cmp_lt_i32_e32 vcc, 6, v100
	v_cmp_gt_i32_e64 s[0:1], 6, v101
	s_or_b64 vcc, vcc, s[0:1]
	v_max3_f32 v104, v102, s41, v103
	v_cndmask_b32_e32 v98, v98, v219, vcc
	v_cmp_lt_i32_e32 vcc, 7, v100
	v_cmp_gt_i32_e64 s[0:1], 7, v101
	v_max3_f32 v104, v104, v105, v106
	s_or_b64 vcc, vcc, s[0:1]
	v_max3_f32 v104, v104, v96, v97
	v_cndmask_b32_e32 v99, v99, v219, vcc
	v_max3_f32 v100, v104, v98, v99
	v_mov_b32_e32 v101, v100
	s_nop 1
	v_permlane16_swap_b32_e32 v100, v101
	v_add_u32_e32 v144, s10, v194
	s_mov_b32 s0, s8
	s_mov_b32 s1, s46
	s_waitcnt lgkmcnt(0)
	v_max_f32_e32 v100, v100, v101
	v_mov_b32_e32 v101, v100
	s_nop 1
	v_permlane32_swap_b32_e32 v100, v101
	s_waitcnt lgkmcnt(0)
	v_max3_f32 v183, v237, v100, v101
	v_sub_f32_e32 v101, v102, v183
	v_exp_f32_e32 v162, v101
	v_sub_f32_e32 v101, v103, v183
	v_sub_f32_e32 v96, v96, v183
	v_exp_f32_e32 v164, v101
	v_sub_f32_e32 v101, v105, v183
	v_exp_f32_e32 v170, v96
	v_sub_f32_e32 v96, v97, v183
	v_exp_f32_e32 v166, v101
	v_sub_f32_e32 v101, v106, v183
	v_exp_f32_e32 v172, v96
	v_sub_f32_e32 v96, v98, v183
	v_exp_f32_e32 v168, v101
	v_exp_f32_e32 v174, v96
	v_sub_f32_e32 v96, v99, v183
	v_exp_f32_e32 v176, v96
	v_pk_add_f32 v[96:97], v[162:163], 0 op_sel_hi:[1,0]
	v_sub_f32_e32 v100, v237, v183
	v_pk_add_f32 v[96:97], v[164:165], v[96:97]
	v_exp_f32_e32 v178, v100
	v_pk_add_f32 v[96:97], v[166:167], v[96:97]
	v_cvt_pk_bf16_f32 v98, v171, v173
	v_pk_add_f32 v[96:97], v[168:169], v[96:97]
	v_cvt_pk_bf16_f32 v99, v175, v177
	v_pk_add_f32 v[96:97], v[170:171], v[96:97]
	v_pk_mul_f32 v[50:51], v[50:51], v[178:179] op_sel_hi:[1,0]
	v_pk_add_f32 v[96:97], v[172:173], v[96:97]
	v_pk_mul_f32 v[48:49], v[48:49], v[178:179] op_sel_hi:[1,0]
	v_pk_add_f32 v[96:97], v[174:175], v[96:97]
	v_pk_mul_f32 v[42:43], v[42:43], v[178:179] op_sel_hi:[1,0]
	v_pk_add_f32 v[100:101], v[176:177], v[96:97]
	v_mov_b32_e32 v96, v179
	v_pk_mul_f32 v[62:63], v[62:63], v[96:97] op_sel_hi:[1,0]
	v_pk_mul_f32 v[60:61], v[60:61], v[96:97] op_sel_hi:[1,0]
	v_pk_mul_f32 v[58:59], v[58:59], v[96:97] op_sel_hi:[1,0]
	v_pk_mul_f32 v[56:57], v[56:57], v[96:97] op_sel_hi:[1,0]
	v_pk_mul_f32 v[54:55], v[54:55], v[96:97] op_sel_hi:[1,0]
	v_pk_mul_f32 v[52:53], v[52:53], v[96:97] op_sel_hi:[1,0]
	v_pk_mul_f32 v[46:47], v[46:47], v[96:97] op_sel_hi:[1,0]
	v_pk_mul_f32 v[44:45], v[44:45], v[96:97] op_sel_hi:[1,0]
	v_cvt_pk_bf16_f32 v96, v163, v165
	v_cvt_pk_bf16_f32 v97, v167, v169
	v_pk_mul_f32 v[40:41], v[40:41], v[178:179] op_sel_hi:[1,0]
	v_pk_mul_f32 v[38:39], v[38:39], v[178:179] op_sel_hi:[1,0]
	v_mfma_f32_16x16x32_bf16 v[60:63], v[64:67], v[96:99], v[60:63]
	v_mul_f32_e64 v36, v36, v178
	v_mul_f32_e64 v37, v37, v178
	v_pk_mul_f32 v[30:31], v[30:31], v[178:179] op_sel_hi:[1,0]
	v_pk_mul_f32 v[28:29], v[28:29], v[178:179] op_sel_hi:[1,0]
	v_cvt_pk_bf16_f32 v64, v162, v164
	v_cvt_pk_bf16_f32 v65, v166, v168
	v_cvt_pk_bf16_f32 v66, v170, v172
	v_cvt_pk_bf16_f32 v67, v174, v176
	v_mfma_f32_16x16x32_bf16 v[56:59], v[68:71], v[96:99], v[56:59]
	v_fma_f32 v160, v160, v178, v100
	v_fma_f32 v161, v161, v179, v101
	s_waitcnt vmcnt(15)
	v_mfma_f32_16x16x32_bf16 v[48:51], v[80:83], v[64:67], v[48:51]
	v_mov_b32_e32 v237, v183
	s_waitcnt vmcnt(14)
	v_mfma_f32_16x16x32_bf16 v[40:43], v[84:87], v[64:67], v[40:43]
	s_waitcnt vmcnt(13)
	v_mfma_f32_16x16x32_bf16 v[36:39], v[88:91], v[64:67], v[36:39]
	s_waitcnt vmcnt(12)
	v_mfma_f32_16x16x32_bf16 v[28:31], v[92:95], v[64:67], v[28:31]
	v_lshrrev_b32_e32 v243, 8, v144
	v_and_b32_e32 v244, 15, v144
	v_lshlrev_b32_e32 v243, 18, v243
	v_lshl_or_b32 v243, v244, 11, v243
	v_bfe_u32 v244, v144, 6, 2
	v_lshl_or_b32 v243, v244, 9, v243
	v_bfe_u32 v244, v144, 4, 2
	v_lshl_or_b32 v64, v244, 5, v243
	v_mov_b32_e32 v65, 0
	v_add_u32_e32 v144, s10, v195
	v_lshl_add_u64 v[64:65], v[154:155], 0, v[64:65]
	v_lshrrev_b32_e32 v243, 8, v144
	v_and_b32_e32 v244, 15, v144
	v_lshlrev_b32_e32 v243, 18, v243
	v_lshl_or_b32 v243, v244, 11, v243
	v_bfe_u32 v244, v144, 6, 2
	v_lshl_or_b32 v243, v244, 9, v243
	v_bfe_u32 v244, v144, 4, 2
	v_lshl_or_b32 v66, v244, 5, v243
	v_mov_b32_e32 v67, 0
	v_mfma_f32_16x16x32_bf16 v[52:55], v[72:75], v[96:99], v[52:55]
	v_lshl_add_u64 v[66:67], v[154:155], 0, v[66:67]
	v_mfma_f32_16x16x32_bf16 v[44:47], v[76:79], v[96:99], v[44:47]
	global_load_dwordx4 v[96:99], v[64:65], off
	global_load_dwordx4 v[100:103], v[64:65], off offset:16
	global_load_dwordx4 v[104:107], v[66:67], off
	global_load_dwordx4 v[108:111], v[66:67], off offset:16
	v_lshl_add_u64 v[64:65], s[20:21], 0, v[192:193]
	v_lshlrev_b64 v[64:65], 9, v[64:65]
	v_lshl_add_u64 v[64:65], v[158:159], 0, v[64:65]
	global_load_dwordx2 v[80:81], v[64:65], off
	global_load_dwordx2 v[82:83], v[64:65], off offset:512
	global_load_dwordx2 v[84:85], v[64:65], off offset:128
	global_load_dwordx2 v[86:87], v[64:65], off offset:640
	global_load_dwordx2 v[88:89], v[64:65], off offset:256
	global_load_dwordx2 v[90:91], v[64:65], off offset:768
	global_load_dwordx2 v[92:93], v[64:65], off offset:384
	global_load_dwordx2 v[94:95], v[64:65], off offset:896
	ds_read_b128 v[64:67], v228 offset:4096
	ds_read_b128 v[68:71], v228 offset:5120
	s_sub_i32 s0, s1, 64
	v_add_u32_e32 v72, s11, v246
	v_lshl_add_u32 v77, v72, 3, s0
	s_waitcnt vmcnt(23) lgkmcnt(1)
; __device__ __forceinline__ void attn_step(int ks, const KVB& b, int L16, int r, int i0, int iq, int lane,
;                                           const bf16x8* qs, f32x4 (&o)[4], float& mrun, float& lrun) {
;   asm volatile("" : "+v"(lane), "+v"(iq));
;   asm volatile("" : "+s"(r), "+s"(i0));
;   const int quad = lane >> 4;
;   bf16x8 qB0 = qs[0], qB1 = qs[64];
;   int cV, sV; attn_desc(ks, quad, r, i0, cV, sV);
;   int D = ks < 12 ? 4 : (ks < 18 ? 16 : 64);
;   f32x4 z = {0.f, 0.f, 0.f, 0.f};
;   f32x4 sa = __builtin_amdgcn_mfma_f32_16x16x32_bf16(b.k0, qB0, z, 0, 0, 0);
;   sa = __builtin_amdgcn_mfma_f32_16x16x32_bf16(b.k1, qB1, sa, 0, 0, 0);
;   f32x4 sb = __builtin_amdgcn_mfma_f32_16x16x32_bf16(b.k2, qB0, z, 0, 0, 0);
;   sb = __builtin_amdgcn_mfma_f32_16x16x32_bf16(b.k3, qB1, sb, 0, 0, 0);
;   int jlo = max(iq - D + (cV < r ? 1 : 0), 0) - sV;
;   int jhi = min(iq + D - (cV > r ? 1 : 0), L16 - 1) - sV;
;   const float NINF = -__builtin_inff();
;   float s8[8];
;   float mt = -1e30f;
; #pragma unroll
;   for (int j = 0; j < 8; ++j) {
;     float sv = j < 4 ? sa[j] : sb[j - 4];
;     sv = (j >= jlo && j <= jhi) ? sv : NINF;
;     s8[j] = sv;
;     mt = fmaxf(mt, sv);
;   }
;   mt = fmaxf(mt, __shfl_xor(mt, 16));
;   mt = fmaxf(mt, __shfl_xor(mt, 32));
;   float mnew = fmaxf(mrun, mt);
;   float alpha = __builtin_amdgcn_exp2f(mrun - mnew);
;   mrun = mnew;
;   float ps = 0.f;
;   float p8[8];
; #pragma unroll
;   for (int j = 0; j < 8; ++j) { p8[j] = __builtin_amdgcn_exp2f(s8[j] - mnew); ps += p8[j]; }
; template <int NT>
; __device__ void attn_unitN(const P& p, int u) {
;     ...
;       { int f = min(e0 + t + 2, EMAX) - 18;
;         bA = attn_load(18 + f / NT, kbase, vbase, L16, rb + RS * (f % NT), i0, lane); }
;       attn_step(ks, bB, L16, rb + RS * (t + 1), i0, iq, lane, qs + (t + 1) * 128, o[t + 1], mrun[t + 1], lrun[t + 1]);
;       { int f = min(e0 + t + 3, EMAX) - 18;
;         bB = attn_load(18 + f / NT, kbase, vbase, L16, rb + RS * (f % NT), i0, lane); }
	v_mfma_f32_16x16x32_bf16 v[72:75], v[112:115], v[64:67], 0
	s_waitcnt vmcnt(21)
	v_mfma_f32_16x16x32_bf16 v[64:67], v[120:123], v[64:67], 0
	s_waitcnt lgkmcnt(0)
	v_mfma_f32_16x16x32_bf16 v[72:75], v[116:119], v[68:71], v[72:75]
	s_waitcnt vmcnt(20)
	v_mfma_f32_16x16x32_bf16 v[64:67], v[124:127], v[68:71], v[64:67]
	v_subrev_u32_e32 v68, 64, v225
	v_add_u32_e32 v69, 64, v225
	v_max_i32_e32 v68, 0, v68
	v_min_i32_e32 v69, s43, v69
	v_sub_u32_e32 v68, v68, v77
	v_sub_u32_e32 v69, v69, v77
	v_cmp_lt_i32_e32 vcc, 0, v68
	v_cmp_gt_i32_e64 s[0:1], 0, v69
	s_or_b64 vcc, vcc, s[0:1]
	v_cndmask_b32_e32 v70, v72, v219, vcc
	v_cmp_lt_i32_e32 vcc, 1, v68
	v_cmp_gt_i32_e64 s[0:1], 1, v69
	s_or_b64 vcc, vcc, s[0:1]
	v_cndmask_b32_e32 v71, v73, v219, vcc
	v_cmp_lt_i32_e32 vcc, 2, v68
	v_cmp_gt_i32_e64 s[0:1], 2, v69
	s_or_b64 vcc, vcc, s[0:1]
	v_cndmask_b32_e32 v73, v74, v219, vcc
	v_cmp_lt_i32_e32 vcc, 3, v68
	v_cmp_gt_i32_e64 s[0:1], 3, v69
	s_or_b64 vcc, vcc, s[0:1]
	v_cndmask_b32_e32 v74, v75, v219, vcc
	v_cmp_lt_i32_e32 vcc, 4, v68
	v_cmp_gt_i32_e64 s[0:1], 4, v69
	s_or_b64 vcc, vcc, s[0:1]
	v_cndmask_b32_e32 v64, v64, v219, vcc
	v_cmp_lt_i32_e32 vcc, 5, v68
	v_cmp_gt_i32_e64 s[0:1], 5, v69
	s_or_b64 vcc, vcc, s[0:1]
	v_cndmask_b32_e32 v65, v65, v219, vcc
	v_cmp_lt_i32_e32 vcc, 6, v68
	v_cmp_gt_i32_e64 s[0:1], 6, v69
	s_or_b64 vcc, vcc, s[0:1]
	v_max3_f32 v72, v70, s41, v71
	v_cndmask_b32_e32 v66, v66, v219, vcc
	v_cmp_lt_i32_e32 vcc, 7, v68
	v_cmp_gt_i32_e64 s[0:1], 7, v69
	v_max3_f32 v72, v72, v73, v74
	s_or_b64 vcc, vcc, s[0:1]
	v_max3_f32 v72, v72, v64, v65
	v_cndmask_b32_e32 v67, v67, v219, vcc
	v_max3_f32 v68, v72, v66, v67
	v_mov_b32_e32 v69, v68
	s_nop 1
	v_permlane16_swap_b32_e32 v68, v69
	s_min_i32 s0, s22, 35
	s_add_i32 s0, s0, -16
	s_ashr_i32 s1, s0, 31
	s_lshr_b32 s1, s1, 30
	s_waitcnt lgkmcnt(0)
	v_max_f32_e32 v68, v68, v69
	v_mov_b32_e32 v69, v68
	s_nop 1
	v_permlane32_swap_b32_e32 v68, v69
	s_add_i32 s1, s0, s1
	s_ashr_i32 s23, s1, 2
	s_and_b32 s1, s1, 0x3ffffffc
	s_sub_i32 s0, s0, s1
	s_waitcnt lgkmcnt(0)
	v_max3_f32 v144, v236, v68, v69
	s_lshl_b32 s0, s0, 2
	v_sub_f32_e32 v69, v70, v144
	v_sub_f32_e32 v64, v64, v144
	s_add_i32 s24, s23, 18
	s_add_i32 s0, s0, s42
	v_exp_f32_e32 v163, v69
	v_sub_f32_e32 v69, v71, v144
	v_exp_f32_e32 v171, v64
	v_sub_f32_e32 v64, v65, v144
	s_cmp_gt_u32 s23, 0xffffffed
	v_exp_f32_e32 v165, v69
	v_sub_f32_e32 v69, v73, v144
	v_exp_f32_e32 v173, v64
	v_sub_f32_e32 v64, v66, v144
	s_cselect_b64 vcc, -1, 0
	s_lshl_b32 s1, s24, 3
	v_exp_f32_e32 v167, v69
	v_sub_f32_e32 v69, v74, v144
	v_exp_f32_e32 v175, v64
	v_sub_f32_e32 v64, v67, v144
	s_add_i32 s1, s1, s47
	s_lshl_b32 s23, s24, 5
	v_exp_f32_e32 v169, v69
	v_exp_f32_e32 v177, v64
	v_add_u32_e32 v64, s23, v231
	v_mov_b32_e32 v69, s1
	v_cndmask_b32_e32 v64, v64, v69, vcc
	v_sub_f32_e32 v68, v236, v144
	v_add_u32_e32 v64, v64, v227
	v_exp_f32_e32 v179, v68
	v_mov_b32_e32 v68, s0
	v_max_i32_e32 v65, 0, v64
	v_max_i32_e32 v64, -4, v64
	v_cndmask_b32_e32 v66, v68, v229, vcc
	v_min_i32_e32 v65, s43, v65
	v_add_u32_e32 v64, 4, v64
	v_min_u32_e32 v67, s43, v64
	v_lshl_add_u32 v64, v65, 4, v66
	v_ashrrev_i32_e32 v65, 31, v64
	v_lshl_add_u32 v66, v67, 4, v66
	v_lshrrev_b32_e32 v243, 8, v64
	v_and_b32_e32 v244, 15, v64
	v_lshlrev_b32_e32 v243, 18, v243
	v_lshl_or_b32 v243, v244, 11, v243
	v_bfe_u32 v244, v64, 6, 2
	v_lshl_or_b32 v243, v244, 9, v243
	v_bfe_u32 v244, v64, 4, 2
	v_lshl_or_b32 v64, v244, 5, v243
	v_mov_b32_e32 v65, 0
	v_ashrrev_i32_e32 v67, 31, v66
	v_lshl_add_u64 v[64:65], v[154:155], 0, v[64:65]
	v_lshrrev_b32_e32 v243, 8, v66
	v_and_b32_e32 v244, 15, v66
	v_lshlrev_b32_e32 v243, 18, v243
	v_lshl_or_b32 v243, v244, 11, v243
	v_bfe_u32 v244, v66, 6, 2
	v_lshl_or_b32 v243, v244, 9, v243
	v_bfe_u32 v244, v66, 4, 2
	v_lshl_or_b32 v66, v244, 5, v243
	v_mov_b32_e32 v67, 0
	v_lshl_add_u64 v[66:67], v[154:155], 0, v[66:67]
	global_load_dwordx4 v[124:127], v[64:65], off
	global_load_dwordx4 v[120:123], v[64:65], off offset:16
	global_load_dwordx4 v[116:119], v[66:67], off
	global_load_dwordx4 v[112:115], v[66:67], off offset:16
	v_add_u32_e32 v65, s23, v232
	v_cndmask_b32_e32 v64, v68, v230, vcc
	v_cndmask_b32_e32 v66, v65, v69, vcc
	v_ashrrev_i32_e32 v65, 31, v64
	v_ashrrev_i32_e32 v66, 2, v66
	v_lshlrev_b64 v[64:65], s44, v[64:65]
	v_ashrrev_i32_e32 v67, 31, v66
	v_lshl_add_u64 v[64:65], v[64:65], 0, v[66:67]
	v_lshlrev_b64 v[64:65], 9, v[64:65]
	v_lshl_add_u64 v[78:79], v[158:159], 0, v[64:65]
	s_mov_b32 s0, s10
	s_mov_b32 s1, s46
	global_load_dwordx2 v[64:65], v[78:79], off
	global_load_dwordx2 v[66:67], v[78:79], off offset:512
	global_load_dwordx2 v[68:69], v[78:79], off offset:128
	global_load_dwordx2 v[70:71], v[78:79], off offset:640
	global_load_dwordx2 v[72:73], v[78:79], off offset:256
	global_load_dwordx2 v[74:75], v[78:79], off offset:768
	global_load_dwordx2 v[76:77], v[78:79], off offset:384
	s_nop 0
	global_load_dwordx2 v[78:79], v[78:79], off offset:896
	ds_read_b128 v[184:187], v228 offset:6144
	ds_read_b128 v[188:191], v228 offset:7168
	s_waitcnt vmcnt(23) lgkmcnt(1)
	v_mfma_f32_16x16x32_bf16 v[96:99], v[96:99], v[184:187], 0
	s_sub_i32 s0, s1, 64
	v_add_u32_e32 v162, s11, v246
	s_waitcnt vmcnt(22) lgkmcnt(0)
	v_mfma_f32_16x16x32_bf16 v[96:99], v[100:103], v[188:191], v[96:99]
	v_lshl_add_u32 v162, v162, 3, s0
	v_mov_b32_e32 v236, v144
	s_waitcnt vmcnt(21)
; __device__ __forceinline__ void attn_step(int ks, const KVB& b, int L16, int r, int i0, int iq, int lane,
;                                           const bf16x8* qs, f32x4 (&o)[4], float& mrun, float& lrun) {
;     ...
;   f32x4 sa = __builtin_amdgcn_mfma_f32_16x16x32_bf16(b.k0, qB0, z, 0, 0, 0);
;   sa = __builtin_amdgcn_mfma_f32_16x16x32_bf16(b.k1, qB1, sa, 0, 0, 0);
;   f32x4 sb = __builtin_amdgcn_mfma_f32_16x16x32_bf16(b.k2, qB0, z, 0, 0, 0);
;   sb = __builtin_amdgcn_mfma_f32_16x16x32_bf16(b.k3, qB1, sb, 0, 0, 0);
;   int jlo = max(iq - D + (cV < r ? 1 : 0), 0) - sV;
;   int jhi = min(iq + D - (cV > r ? 1 : 0), L16 - 1) - sV;
;   const float NINF = -__builtin_inff();
;   float s8[8];
;   float mt = -1e30f;
; #pragma unroll
;   for (int j = 0; j < 8; ++j) {
;     float sv = j < 4 ? sa[j] : sb[j - 4];
;     sv = (j >= jlo && j <= jhi) ? sv : NINF;
;     s8[j] = sv;
;     mt = fmaxf(mt, sv);
;   }
;   mt = fmaxf(mt, __shfl_xor(mt, 16));
;   mt = fmaxf(mt, __shfl_xor(mt, 32));
;   float mnew = fmaxf(mrun, mt);
;   float alpha = __builtin_amdgcn_exp2f(mrun - mnew);
;   mrun = mnew;
;   float ps = 0.f;
;   float p8[8];
; #pragma unroll
;   for (int j = 0; j < 8; ++j) { p8[j] = __builtin_amdgcn_exp2f(s8[j] - mnew); ps += p8[j]; }
;   lrun = lrun * alpha + ps;
;   union { uint4 u; bf16x8 v; } pb;
;   pb.u = make_uint4(pack2(p8[0], p8[1]), pack2(p8[2], p8[3]), pack2(p8[4], p8[5]), pack2(p8[6], p8[7]));
; #pragma unroll
;   for (int dt = 0; dt < 4; ++dt) { o[dt][0] *= alpha; o[dt][1] *= alpha; o[dt][2] *= alpha; o[dt][3] *= alpha; }
;   o[0] = __builtin_amdgcn_mfma_f32_16x16x32_bf16(b.v0, pb.v, o[0], 0, 0, 0);
;   o[1] = __builtin_amdgcn_mfma_f32_16x16x32_bf16(b.v1, pb.v, o[1], 0, 0, 0);
;   o[2] = __builtin_amdgcn_mfma_f32_16x16x32_bf16(b.v2, pb.v, o[2], 0, 0, 0);
;   o[3] = __builtin_amdgcn_mfma_f32_16x16x32_bf16(b.v3, pb.v, o[3], 0, 0, 0);
; template <int NT>
; __device__ void attn_unitN(const P& p, int u) {
;     ...
;   for (int kk = 0; kk < 5; ++kk) {
;     int e0 = 18 + NT * kk, ks = 18 + kk;
; #pragma unroll
;     for (int t = 0; t < NT; t += 2) {
;       attn_step(ks, bA, L16, rb + RS * t, i0, iq, lane, qs + t * 128, o[t], mrun[t], lrun[t]);
;       { int f = min(e0 + t + 2, EMAX) - 18;
;         bA = attn_load(18 + f / NT, kbase, vbase, L16, rb + RS * (f % NT), i0, lane); }
	v_mfma_f32_16x16x32_bf16 v[100:103], v[104:107], v[184:187], 0
	v_subrev_u32_e32 v104, 64, v225
	v_add_u32_e32 v105, 64, v225
	v_max_i32_e32 v104, 0, v104
	v_min_i32_e32 v105, s43, v105
	v_sub_u32_e32 v104, v104, v162
	v_sub_u32_e32 v105, v105, v162
	v_cmp_lt_i32_e32 vcc, 0, v104
	v_cmp_gt_i32_e64 s[0:1], 0, v105
	s_or_b64 vcc, vcc, s[0:1]
	v_cndmask_b32_e32 v96, v96, v219, vcc
	v_cmp_lt_i32_e32 vcc, 1, v104
	v_cmp_gt_i32_e64 s[0:1], 1, v105
	s_or_b64 vcc, vcc, s[0:1]
	v_cndmask_b32_e32 v97, v97, v219, vcc
	v_cmp_lt_i32_e32 vcc, 2, v104
	v_cmp_gt_i32_e64 s[0:1], 2, v105
	s_or_b64 vcc, vcc, s[0:1]
	s_waitcnt vmcnt(20)
	v_mfma_f32_16x16x32_bf16 v[100:103], v[108:111], v[188:191], v[100:103]
	v_cndmask_b32_e32 v98, v98, v219, vcc
	v_cmp_lt_i32_e32 vcc, 3, v104
	v_cmp_gt_i32_e64 s[0:1], 3, v105
	s_or_b64 vcc, vcc, s[0:1]
	v_cndmask_b32_e32 v99, v99, v219, vcc
	v_cmp_lt_i32_e32 vcc, 4, v104
	v_cmp_gt_i32_e64 s[0:1], 4, v105
	s_or_b64 vcc, vcc, s[0:1]
	v_cndmask_b32_e32 v100, v100, v219, vcc
	v_cmp_lt_i32_e32 vcc, 5, v104
	v_cmp_gt_i32_e64 s[0:1], 5, v105
	s_or_b64 vcc, vcc, s[0:1]
	v_cndmask_b32_e32 v101, v101, v219, vcc
	v_cmp_lt_i32_e32 vcc, 6, v104
	v_cmp_gt_i32_e64 s[0:1], 6, v105
	s_or_b64 vcc, vcc, s[0:1]
	v_max3_f32 v106, v96, s41, v97
	v_cndmask_b32_e32 v102, v102, v219, vcc
	v_cmp_lt_i32_e32 vcc, 7, v104
	v_cmp_gt_i32_e64 s[0:1], 7, v105
	v_max3_f32 v106, v106, v98, v99
	s_or_b64 vcc, vcc, s[0:1]
	v_max3_f32 v106, v106, v100, v101
	v_cndmask_b32_e32 v103, v103, v219, vcc
	v_max3_f32 v104, v106, v102, v103
	v_mov_b32_e32 v105, v104
	s_nop 1
	v_permlane16_swap_b32_e32 v104, v105
	s_min_i32 s0, s22, 34
	s_add_i32 s0, s0, -15
	s_ashr_i32 s1, s0, 31
	s_lshr_b32 s1, s1, 30
	s_waitcnt lgkmcnt(0)
	v_max_f32_e32 v104, v104, v105
	v_mov_b32_e32 v105, v104
	s_nop 1
	v_permlane32_swap_b32_e32 v104, v105
	s_add_i32 s1, s0, s1
	s_ashr_i32 s22, s1, 2
	s_and_b32 s1, s1, 0x3ffffffc
	s_sub_i32 s0, s0, s1
	s_waitcnt lgkmcnt(0)
	v_max3_f32 v184, v235, v104, v105
	v_sub_f32_e32 v96, v96, v184
	v_exp_f32_e32 v162, v96
	v_sub_f32_e32 v96, v97, v184
	v_exp_f32_e32 v164, v96
	v_sub_f32_e32 v96, v98, v184
	v_exp_f32_e32 v166, v96
	v_sub_f32_e32 v96, v99, v184
	v_exp_f32_e32 v168, v96
	v_sub_f32_e32 v96, v100, v184
	v_exp_f32_e32 v170, v96
	v_sub_f32_e32 v96, v101, v184
	v_exp_f32_e32 v172, v96
	v_sub_f32_e32 v96, v102, v184
	v_exp_f32_e32 v174, v96
	v_sub_f32_e32 v96, v103, v184
	v_exp_f32_e32 v176, v96
	v_pk_add_f32 v[96:97], v[162:163], 0 op_sel_hi:[1,0]
	v_sub_f32_e32 v104, v235, v184
	v_pk_add_f32 v[96:97], v[164:165], v[96:97]
	v_exp_f32_e32 v178, v104
	v_pk_add_f32 v[96:97], v[166:167], v[96:97]
	s_lshl_b32 s0, s0, 2
	v_pk_add_f32 v[96:97], v[168:169], v[96:97]
	s_add_i32 s23, s22, 18
	v_pk_add_f32 v[96:97], v[170:171], v[96:97]
	s_add_i32 s0, s0, s42
	v_pk_add_f32 v[96:97], v[172:173], v[96:97]
	s_cmp_gt_u32 s22, 0xffffffed
	v_pk_add_f32 v[96:97], v[174:175], v[96:97]
	v_cvt_pk_bf16_f32 v98, v171, v173
	v_pk_add_f32 v[100:101], v[176:177], v[96:97]
	v_mov_b32_e32 v96, v179
	v_pk_mul_f32 v[34:35], v[34:35], v[96:97] op_sel_hi:[1,0]
	v_pk_mul_f32 v[32:33], v[32:33], v[96:97] op_sel_hi:[1,0]
	v_pk_mul_f32 v[26:27], v[26:27], v[96:97] op_sel_hi:[1,0]
	v_pk_mul_f32 v[24:25], v[24:25], v[96:97] op_sel_hi:[1,0]
	v_pk_mul_f32 v[22:23], v[22:23], v[96:97] op_sel_hi:[1,0]
	v_pk_mul_f32 v[20:21], v[20:21], v[96:97] op_sel_hi:[1,0]
	v_pk_mul_f32 v[14:15], v[14:15], v[96:97] op_sel_hi:[1,0]
	v_pk_mul_f32 v[12:13], v[12:13], v[96:97] op_sel_hi:[1,0]
	v_cvt_pk_bf16_f32 v96, v163, v165
	v_cvt_pk_bf16_f32 v97, v167, v169
	v_cvt_pk_bf16_f32 v99, v175, v177
	s_cselect_b64 vcc, -1, 0
	s_lshl_b32 s1, s23, 3
	v_mfma_f32_16x16x32_bf16 v[32:35], v[128:131], v[96:99], v[32:35]
	v_mul_f32_e64 v18, v18, v178
	v_mul_f32_e64 v19, v19, v178
	v_pk_mul_f32 v[16:17], v[16:17], v[178:179] op_sel_hi:[1,0]
	v_pk_mul_f32 v[10:11], v[10:11], v[178:179] op_sel_hi:[1,0]
	v_mfma_f32_16x16x32_bf16 v[24:27], v[132:135], v[96:99], v[24:27]
	v_mul_f32_e64 v8, v8, v178
	v_mul_f32_e64 v9, v9, v178
	s_add_i32 s1, s1, s47
	s_lshl_b32 s22, s23, 5
	v_mfma_f32_16x16x32_bf16 v[20:23], v[136:139], v[96:99], v[20:23]
	v_mul_f32_e64 v6, v6, v178
	v_mul_f32_e64 v7, v7, v178
	v_pk_mul_f32 v[4:5], v[4:5], v[178:179] op_sel_hi:[1,0]
	v_pk_mul_f32 v[2:3], v[2:3], v[178:179] op_sel_hi:[1,0]
	v_mfma_f32_16x16x32_bf16 v[12:15], v[140:143], v[96:99], v[12:15]
	v_cvt_pk_bf16_f32 v96, v162, v164
	v_cvt_pk_bf16_f32 v97, v166, v168
	v_cvt_pk_bf16_f32 v98, v170, v172
	v_cvt_pk_bf16_f32 v99, v174, v176
	v_pk_mul_f32 v[0:1], v[0:1], v[178:179] op_sel_hi:[1,0]
	v_pk_fma_f32 v[156:157], v[156:157], v[178:179], v[100:101]
	s_waitcnt vmcnt(18)
	v_mfma_f32_16x16x32_bf16 v[16:19], v[80:83], v[96:99], v[16:19]
	v_add_u32_e32 v80, s22, v231
	s_add_i32 s11, s11, 4
	s_cmp_lg_u32 s11, 20
	s_waitcnt vmcnt(16)
	v_mfma_f32_16x16x32_bf16 v[8:11], v[84:87], v[96:99], v[8:11]
	v_mov_b32_e32 v85, s1
	v_cndmask_b32_e32 v80, v80, v85, vcc
	v_add_u32_e32 v80, v80, v227
	v_mov_b32_e32 v84, s0
	v_max_i32_e32 v81, 0, v80
	v_max_i32_e32 v80, -4, v80
	v_cndmask_b32_e32 v82, v84, v229, vcc
	v_min_i32_e32 v81, s43, v81
	v_add_u32_e32 v80, 4, v80
	v_min_u32_e32 v83, s43, v80
	v_lshl_add_u32 v80, v81, 4, v82
	v_ashrrev_i32_e32 v81, 31, v80
	v_lshl_add_u32 v82, v83, 4, v82
	v_lshrrev_b32_e32 v243, 8, v80
	v_and_b32_e32 v244, 15, v80
	v_lshlrev_b32_e32 v243, 18, v243
	v_lshl_or_b32 v243, v244, 11, v243
	v_bfe_u32 v244, v80, 6, 2
	v_lshl_or_b32 v243, v244, 9, v243
	v_bfe_u32 v244, v80, 4, 2
	v_lshl_or_b32 v80, v244, 5, v243
	v_mov_b32_e32 v81, 0
	v_ashrrev_i32_e32 v83, 31, v82
	v_lshl_add_u64 v[80:81], v[154:155], 0, v[80:81]
	v_lshrrev_b32_e32 v243, 8, v82
	v_and_b32_e32 v244, 15, v82
	v_lshlrev_b32_e32 v243, 18, v243
	v_lshl_or_b32 v243, v244, 11, v243
	v_bfe_u32 v244, v82, 6, 2
	v_lshl_or_b32 v243, v244, 9, v243
	v_bfe_u32 v244, v82, 4, 2
	v_lshl_or_b32 v82, v244, 5, v243
	v_mov_b32_e32 v83, 0
	s_waitcnt vmcnt(14)
; template <int NT>
; __device__ void attn_unitN(const P& p, int u) {
;     ...
;       { int f = min(e0 + t + 3, EMAX) - 18;
;         bB = attn_load(18 + f / NT, kbase, vbase, L16, rb + RS * (f % NT), i0, lane); }
;     }
	v_mfma_f32_16x16x32_bf16 v[4:7], v[88:91], v[96:99], v[4:7]
	v_lshl_add_u64 v[82:83], v[154:155], 0, v[82:83]
	v_mov_b32_e32 v235, v184
	v_mov_b32_e32 v143, v182
	s_waitcnt vmcnt(12)
	v_mfma_f32_16x16x32_bf16 v[0:3], v[92:95], v[96:99], v[0:3]
	global_load_dwordx4 v[108:111], v[80:81], off
	global_load_dwordx4 v[104:107], v[80:81], off offset:16
	global_load_dwordx4 v[100:103], v[82:83], off
	global_load_dwordx4 v[96:99], v[82:83], off offset:16
	v_add_u32_e32 v81, s22, v232
	v_cndmask_b32_e32 v80, v84, v230, vcc
	v_cndmask_b32_e32 v82, v81, v85, vcc
	v_ashrrev_i32_e32 v81, 31, v80
	v_ashrrev_i32_e32 v82, 2, v82
	v_lshlrev_b64 v[80:81], s44, v[80:81]
	v_ashrrev_i32_e32 v83, 31, v82
	v_lshl_add_u64 v[80:81], v[80:81], 0, v[82:83]
	v_lshlrev_b64 v[80:81], 9, v[80:81]
	v_lshl_add_u64 v[94:95], v[158:159], 0, v[80:81]
	global_load_dwordx2 v[80:81], v[94:95], off
	global_load_dwordx2 v[82:83], v[94:95], off offset:512
	global_load_dwordx2 v[84:85], v[94:95], off offset:128
	global_load_dwordx2 v[86:87], v[94:95], off offset:640
	global_load_dwordx2 v[88:89], v[94:95], off offset:256
	global_load_dwordx2 v[90:91], v[94:95], off offset:768
	global_load_dwordx2 v[92:93], v[94:95], off offset:384
	s_nop 0
	global_load_dwordx2 v[94:95], v[94:95], off offset:896
	s_cbranch_scc1 .LBB0_267
; template <int NT>
; __device__ void attn_unitN(const P& p, int u) {
;     ...
;   u16* omix = (u16*)(p.ws + OFF_OMIX);
; #pragma unroll
;   for (int t = 0; t < NT; ++t) {
;     float l = lrun[t];
;     l += __shfl_xor(l, 16);
;     l += __shfl_xor(l, 32);
;     float inv = 1.f / l;
;     u16* op = omix + (size_t)(seq0 + rb + RS * t + 16 * iq) * 1024 + h * 64 + quad * 4;
; #pragma unroll
;     for (int dt = 0; dt < 4; ++dt) {
;       uint2 w; w.x = pack2(o[t][dt][0] * inv, o[t][dt][1] * inv); w.y = pack2(o[t][dt][2] * inv, o[t][dt][3] * inv);
;       *(uint2*)(op + dt * 16) = w;
;     }
;   }
; }
; __device__ void phase_attn(const P& p) {
;   int wid = __builtin_amdgcn_readfirstlane(opaque_tid(p) >> 6);
;   for (int u = blockIdx.x * 8 + wid; u < 32768 / ATT_NT; u += gridDim.x * 8) attn_unitN<ATT_NT>(p, u);
	s_waitcnt vmcnt(19)
	ds_bpermute_b32 v64, v233, v161
	s_lshl_b32 s0, s45, 1
	s_waitcnt vmcnt(18)
	v_lshrrev_b32_e32 v66, 1, v224
	s_add_u32 s0, s34, s0
	v_and_b32_e32 v144, 24, v66
	s_waitcnt lgkmcnt(0)
	v_add_f32_e32 v67, v161, v64
	s_waitcnt vmcnt(17)
	ds_bpermute_b32 v68, v234, v67
	s_addc_u32 s1, s35, 0
	v_lshlrev_b64 v[64:65], 11, v[152:153]
	s_add_i32 s3, s3, s30
	s_cmpk_lt_i32 s3, 0x2000
	s_waitcnt lgkmcnt(0)
	v_add_f32_e32 v68, v67, v68
	v_div_scale_f32 v69, s[4:5], v68, v68, 1.0
	s_waitcnt vmcnt(16)
	v_rcp_f32_e32 v70, v69
	v_div_scale_f32 v71, vcc, 1.0, v68, 1.0
	v_lshl_add_u64 v[66:67], s[0:1], 0, v[144:145]
	s_waitcnt vmcnt(15)
	v_fma_f32 v72, -v69, v70, 1.0
	v_fmac_f32_e32 v70, v72, v70
	v_mul_f32_e32 v72, v71, v70
	v_fma_f32 v73, -v69, v72, v71
	v_fmac_f32_e32 v72, v73, v70
	v_fma_f32 v69, -v69, v72, v71
	v_div_fmas_f32 v69, v69, v70, v72
	v_div_fixup_f32 v68, v69, v68, 1.0
	v_pk_mul_f32 v[56:57], v[56:57], v[68:69] op_sel_hi:[1,0]
	v_pk_mul_f32 v[58:59], v[58:59], v[68:69] op_sel_hi:[1,0]
	v_cvt_pk_bf16_f32 v56, v56, v57
	v_cvt_pk_bf16_f32 v57, v58, v59
	ds_bpermute_b32 v58, v233, v160
	v_lshl_add_u64 v[64:65], v[66:67], 0, v[64:65]
	global_store_dwordx2 v[64:65], v[56:57], off offset:32
	v_pk_mul_f32 v[52:53], v[52:53], v[68:69] op_sel_hi:[1,0]
	v_pk_mul_f32 v[54:55], v[54:55], v[68:69] op_sel_hi:[1,0]
	s_waitcnt lgkmcnt(0)
	v_add_f32_e32 v56, v160, v58
	ds_bpermute_b32 v57, v234, v56
	v_cvt_pk_bf16_f32 v52, v52, v53
	v_cvt_pk_bf16_f32 v53, v54, v55
	global_store_dwordx2 v[64:65], v[52:53], off offset:64
	v_pk_mul_f32 v[44:45], v[44:45], v[68:69] op_sel_hi:[1,0]
	s_waitcnt lgkmcnt(0)
	v_add_f32_e32 v52, v56, v57
	v_div_scale_f32 v53, s[0:1], v52, v52, 1.0
	v_rcp_f32_e32 v54, v53
	v_pk_mul_f32 v[46:47], v[46:47], v[68:69] op_sel_hi:[1,0]
	v_cvt_pk_bf16_f32 v44, v44, v45
	v_cvt_pk_bf16_f32 v45, v46, v47
	global_store_dwordx2 v[64:65], v[44:45], off offset:96
	v_fma_f32 v44, -v53, v54, 1.0
	v_fmac_f32_e32 v54, v44, v54
	v_div_scale_f32 v44, vcc, 1.0, v52, 1.0
	v_mul_f32_e32 v45, v44, v54
	v_fma_f32 v46, -v53, v45, v44
	v_fmac_f32_e32 v45, v46, v54
	v_fma_f32 v44, -v53, v45, v44
	v_div_fmas_f32 v44, v44, v54, v45
	v_div_fixup_f32 v44, v44, v52, 1.0
	v_pk_mul_f32 v[40:41], v[40:41], v[44:45] op_sel_hi:[1,0]
	v_pk_mul_f32 v[42:43], v[42:43], v[44:45] op_sel_hi:[1,0]
	v_cvt_pk_bf16_f32 v40, v40, v41
	v_cvt_pk_bf16_f32 v41, v42, v43
	ds_bpermute_b32 v42, v233, v157
	v_lshlrev_b64 v[46:47], 11, v[150:151]
	v_lshl_add_u64 v[46:47], v[66:67], 0, v[46:47]
	global_store_dwordx2 v[46:47], v[40:41], off offset:32
	v_pk_mul_f32 v[36:37], v[36:37], v[44:45] op_sel_hi:[1,0]
	s_waitcnt lgkmcnt(0)
	v_add_f32_e32 v40, v157, v42
	ds_bpermute_b32 v41, v234, v40
	v_pk_mul_f32 v[38:39], v[38:39], v[44:45] op_sel_hi:[1,0]
	v_cvt_pk_bf16_f32 v36, v36, v37
	v_cvt_pk_bf16_f32 v37, v38, v39
	global_store_dwordx2 v[46:47], v[36:37], off offset:64
	s_waitcnt lgkmcnt(0)
	v_add_f32_e32 v36, v40, v41
	v_div_scale_f32 v37, s[0:1], v36, v36, 1.0
	v_rcp_f32_e32 v38, v37
	v_pk_mul_f32 v[28:29], v[28:29], v[44:45] op_sel_hi:[1,0]
	v_pk_mul_f32 v[30:31], v[30:31], v[44:45] op_sel_hi:[1,0]
	v_cvt_pk_bf16_f32 v28, v28, v29
	v_cvt_pk_bf16_f32 v29, v30, v31
	global_store_dwordx2 v[46:47], v[28:29], off offset:96
	v_fma_f32 v28, -v37, v38, 1.0
	v_fmac_f32_e32 v38, v28, v38
	v_div_scale_f32 v28, vcc, 1.0, v36, 1.0
	v_mul_f32_e32 v29, v28, v38
	v_fma_f32 v30, -v37, v29, v28
	v_fmac_f32_e32 v29, v30, v38
	v_fma_f32 v28, -v37, v29, v28
	v_div_fmas_f32 v28, v28, v38, v29
	v_div_fixup_f32 v28, v28, v36, 1.0
	v_pk_mul_f32 v[24:25], v[24:25], v[28:29] op_sel_hi:[1,0]
	v_pk_mul_f32 v[26:27], v[26:27], v[28:29] op_sel_hi:[1,0]
	v_cvt_pk_bf16_f32 v24, v24, v25
	v_cvt_pk_bf16_f32 v25, v26, v27
	ds_bpermute_b32 v26, v233, v156
	v_lshlrev_b64 v[30:31], 11, v[148:149]
	v_lshl_add_u64 v[30:31], v[66:67], 0, v[30:31]
	global_store_dwordx2 v[30:31], v[24:25], off offset:32
	v_pk_mul_f32 v[20:21], v[20:21], v[28:29] op_sel_hi:[1,0]
	s_waitcnt lgkmcnt(0)
	v_add_f32_e32 v24, v156, v26
	ds_bpermute_b32 v25, v234, v24
	v_pk_mul_f32 v[22:23], v[22:23], v[28:29] op_sel_hi:[1,0]
	v_cvt_pk_bf16_f32 v20, v20, v21
	v_cvt_pk_bf16_f32 v21, v22, v23
	global_store_dwordx2 v[30:31], v[20:21], off offset:64
	s_waitcnt lgkmcnt(0)
	v_add_f32_e32 v20, v24, v25
	v_div_scale_f32 v21, s[0:1], v20, v20, 1.0
	v_rcp_f32_e32 v22, v21
	v_pk_mul_f32 v[12:13], v[12:13], v[28:29] op_sel_hi:[1,0]
	v_pk_mul_f32 v[14:15], v[14:15], v[28:29] op_sel_hi:[1,0]
	v_cvt_pk_bf16_f32 v12, v12, v13
	v_cvt_pk_bf16_f32 v13, v14, v15
	global_store_dwordx2 v[30:31], v[12:13], off offset:96
	v_fma_f32 v12, -v21, v22, 1.0
	v_fmac_f32_e32 v22, v12, v22
	v_div_scale_f32 v12, vcc, 1.0, v20, 1.0
	v_mul_f32_e32 v13, v12, v22
	v_fma_f32 v14, -v21, v13, v12
	v_fmac_f32_e32 v13, v14, v22
	v_fma_f32 v12, -v21, v13, v12
	v_div_fmas_f32 v12, v12, v22, v13
	v_div_fixup_f32 v12, v12, v20, 1.0
	v_pk_mul_f32 v[60:61], v[60:61], v[68:69] op_sel_hi:[1,0]
	v_pk_mul_f32 v[62:63], v[62:63], v[68:69] op_sel_hi:[1,0]
	v_pk_mul_f32 v[48:49], v[48:49], v[44:45] op_sel_hi:[1,0]
	v_pk_mul_f32 v[50:51], v[50:51], v[44:45] op_sel_hi:[1,0]
	v_pk_mul_f32 v[32:33], v[32:33], v[28:29] op_sel_hi:[1,0]
	v_pk_mul_f32 v[34:35], v[34:35], v[28:29] op_sel_hi:[1,0]
	v_lshlrev_b64 v[14:15], 11, v[146:147]
	v_pk_mul_f32 v[16:17], v[16:17], v[12:13] op_sel_hi:[1,0]
	v_pk_mul_f32 v[18:19], v[18:19], v[12:13] op_sel_hi:[1,0]
	v_pk_mul_f32 v[8:9], v[8:9], v[12:13] op_sel_hi:[1,0]
	v_pk_mul_f32 v[10:11], v[10:11], v[12:13] op_sel_hi:[1,0]
	v_pk_mul_f32 v[4:5], v[4:5], v[12:13] op_sel_hi:[1,0]
	v_pk_mul_f32 v[6:7], v[6:7], v[12:13] op_sel_hi:[1,0]
	v_pk_mul_f32 v[0:1], v[0:1], v[12:13] op_sel_hi:[1,0]
	v_pk_mul_f32 v[2:3], v[2:3], v[12:13] op_sel_hi:[1,0]
	v_cvt_pk_bf16_f32 v60, v60, v61
	v_cvt_pk_bf16_f32 v61, v62, v63
	v_cvt_pk_bf16_f32 v48, v48, v49
	v_cvt_pk_bf16_f32 v49, v50, v51
	v_cvt_pk_bf16_f32 v32, v32, v33
	v_cvt_pk_bf16_f32 v33, v34, v35
	v_lshl_add_u64 v[14:15], v[66:67], 0, v[14:15]
	v_cvt_pk_bf16_f32 v16, v16, v17
	v_cvt_pk_bf16_f32 v17, v18, v19
	v_cvt_pk_bf16_f32 v8, v8, v9
	v_cvt_pk_bf16_f32 v9, v10, v11
	v_cvt_pk_bf16_f32 v4, v4, v5
	v_cvt_pk_bf16_f32 v5, v6, v7
	v_cvt_pk_bf16_f32 v0, v0, v1
	v_cvt_pk_bf16_f32 v1, v2, v3
	global_store_dwordx2 v[64:65], v[60:61], off
	global_store_dwordx2 v[46:47], v[48:49], off
	global_store_dwordx2 v[30:31], v[32:33], off
	global_store_dwordx2 v[14:15], v[16:17], off
	global_store_dwordx2 v[14:15], v[8:9], off offset:32
	global_store_dwordx2 v[14:15], v[4:5], off offset:64
	global_store_dwordx2 v[14:15], v[0:1], off offset:96
	s_cbranch_scc1 .LBB0_231
